# residual phases: non-meta workgroups start 4us later so the meta-row partial sums run on an unloaded memory system; partial sums 24 loads deep
# speedup vs baseline: 1.0010x; 1.0010x over previous
; __device__ __forceinline__ int opaque_tid() { int t = threadIdx.x; asm volatile("" : "+v"(t)); return t; }
; __device__ __forceinline__ void phase_resid(const Params& p, const float* g, bool first, bool last, int nsplit) {
;     const int tid = opaque_tid(), lane = tid & 63, gw = (blockIdx.x * NTHREADS + tid) >> 6, nw = (gridDim.x * NTHREADS) >> 6;
;     float* h = (float*)(p.ws + WS_H); bf16_t* abf = (bf16_t*)(p.ws + WS_ABF);
;     const bf16_t* mix = (const bf16_t*)(p.ws + WS_MIX);
;     const float* part = (const float*)(p.ws + WS_PART);
;     f32x4 gv[8];
; #pragma unroll
;     for (int i = 0; i < 8; ++i) gv[i] = *(const f32x4*)(g + lane * 4 + 256 * i);
;     ...
;     if (gw < 16) {
;         const int row = PADR + gw;
;         f32x4 mv[8], hv[8];
; #pragma unroll
;         for (int i = 0; i < 8; ++i) { mv[i] = (f32x4){0.f, 0.f, 0.f, 0.f}; hv[i] = *(const f32x4*)(HROW(row) + lane * 4 + 256 * i); }
;         for (int sp = 0; sp < nsplit; ++sp) {
; #pragma unroll
;             for (int i = 0; i < 8; ++i) mv[i] += *(const f32x4*)(part + (size_t)(sp * 16 + gw) * DM + lane * 4 + 256 * i);
;         }
.LBB0_300:
	v_writelane_b32 v254, s49, 28
	v_writelane_b32 v254, s48, 29
	v_writelane_b32 v254, s45, 30
	v_writelane_b32 v254, s44, 31
	v_writelane_b32 v254, s43, 32
	v_writelane_b32 v254, s42, 33
	v_writelane_b32 v254, s37, 34
	v_writelane_b32 v254, s36, 35
	v_writelane_b32 v254, s33, 36
	v_writelane_b32 v254, s29, 37
	v_writelane_b32 v254, s22, 38
	s_ashr_i32 s91, s90, 31
	s_nop 0
	v_writelane_b32 v254, s23, 39
	v_writelane_b32 v254, s21, 40
	v_writelane_b32 v254, s20, 41
	v_writelane_b32 v254, s19, 42
	v_writelane_b32 v254, s18, 43
	v_writelane_b32 v254, s17, 44
	v_writelane_b32 v254, s16, 45
	v_writelane_b32 v254, s12, 46
	v_writelane_b32 v254, s11, 47
	v_writelane_b32 v254, s10, 48
	v_writelane_b32 v254, s9, 49
	v_writelane_b32 v254, s8, 50
	v_writelane_b32 v254, s7, 51
	v_writelane_b32 v254, s5, 52
	s_mul_i32 s5, s90, 0x6280000
	v_writelane_b32 v254, s4, 53
	s_mul_hi_i32 s4, s90, 0x6280000
	s_add_u32 s5, s34, s5
	v_writelane_b32 v254, s5, 54
	s_addc_u32 s4, s35, s4
	v_writelane_b32 v254, s4, 55
	v_writelane_b32 v254, s50, 56
	s_cmp_lt_i32 s50, 5
	s_mov_b64 s[4:5], -1
	v_writelane_b32 v254, s31, 57
	s_cbranch_scc1 .LBB0_763
	v_readlane_b32 s4, v254, 56
	s_cmp_lt_i32 s4, 7
	s_mov_b64 s[4:5], -1
	s_cbranch_scc1 .LBB0_382
	v_readlane_b32 s4, v254, 56
	s_cmp_gt_i32 s4, 7
	s_mov_b64 s[4:5], -1
	s_cbranch_scc0 .LBB0_350
	s_cmp_lt_u32 s80, 2
	s_cbranch_scc1 .Lrd_p8
	s_sleep 127
.Lrd_p8:
	s_lshl_b32 s4, s90, 11
	s_ashr_i32 s5, s4, 31
	v_mov_b32_e32 v34, v210
	s_lshl_b64 s[4:5], s[4:5], 2
	s_add_u32 s4, s6, s4
	v_lshlrev_b32_e32 v0, 2, v34
	v_and_b32_e32 v116, 0xfc, v0
	s_addc_u32 s5, s3, s5
	v_lshlrev_b32_e32 v0, 2, v116
	v_lshl_add_u64 v[18:19], s[4:5], 0, v[0:1]
	v_add_co_u32_e32 v30, vcc, 0x1000, v18
	global_load_dwordx4 v[2:5], v0, s[4:5]
	global_load_dwordx4 v[6:9], v0, s[4:5] offset:1024
	global_load_dwordx4 v[10:13], v0, s[4:5] offset:2048
	global_load_dwordx4 v[14:17], v0, s[4:5] offset:3072
	v_addc_co_u32_e32 v31, vcc, 0, v19, vcc
	global_load_dwordx4 v[18:21], v[30:31], off
	global_load_dwordx4 v[22:25], v[30:31], off offset:1024
	global_load_dwordx4 v[26:29], v[30:31], off offset:2048
	s_nop 0
	global_load_dwordx4 v[30:33], v[30:31], off offset:3072
	s_sub_i32 s3, s31, 28
	s_cmp_lt_u32 s3, 9
	s_cselect_b64 s[4:5], -1, 0
	s_cmp_gt_u32 s3, 8
	v_readlane_b32 s3, v252, 5
	s_cselect_b64 s[8:9], -1, 0
	s_add_u32 s16, s34, 0x18a00000
	v_add_u32_e32 v35, s3, v34
	s_movk_i32 s3, 0x400
	s_addc_u32 s17, s35, 0
	v_lshrrev_b32_e32 v70, 6, v35
	v_cmp_gt_u32_e32 vcc, s3, v35
	v_and_b32_e32 v148, 63, v34
	s_and_saveexec_b64 s[10:11], vcc
	v_readlane_b32 s12, v254, 5
	s_mov_b32 s3, 0x415c8000
	s_mov_b32 s20, 0x415c9000
	s_mov_b32 s21, 0x415ca000
	s_mov_b32 s22, 0x415e8000
	s_mov_b32 s23, 0x415e9000
	s_mov_b32 s25, 0x415ea000
	s_cbranch_execz .LBB0_308
	v_mov_b32_e32 v34, 0x78000
	v_lshl_or_b32 v66, v70, 11, v34
	v_mov_b32_e32 v67, v1
	v_lshl_add_u64 v[34:35], v[66:67], 2, s[16:17]
	v_lshl_add_u64 v[68:69], v[34:35], 0, v[0:1]
	v_add_co_u32_e32 v34, vcc, 0x1000, v68
	global_load_dwordx4 v[62:65], v[68:69], off
	global_load_dwordx4 v[58:61], v[68:69], off offset:1024
	global_load_dwordx4 v[54:57], v[68:69], off offset:2048
	global_load_dwordx4 v[50:53], v[68:69], off offset:3072
	v_addc_co_u32_e32 v35, vcc, 0, v69, vcc
	global_load_dwordx4 v[46:49], v[34:35], off
	global_load_dwordx4 v[42:45], v[34:35], off offset:1024
	global_load_dwordx4 v[38:41], v[34:35], off offset:2048
	s_nop 0
	global_load_dwordx4 v[34:37], v[34:35], off offset:3072
	s_mov_b64 s[6:7], 0x1000
	v_lshl_add_u64 v[78:79], v[68:69], 0, s[6:7]
	s_mov_b64 s[6:7], 0x1400
	v_mov_b32_e32 v71, v1
	v_lshl_add_u64 v[72:73], v[68:69], 0, s[6:7]
	s_mov_b64 s[6:7], 0x1800
	v_lshlrev_b64 v[80:81], 13, v[70:71]
	v_lshl_add_u64 v[74:75], v[68:69], 0, s[6:7]
	s_mov_b64 s[6:7], 0x1c00
	v_lshl_or_b32 v80, v148, 4, v80
	v_mov_b32_e32 v88, 0
	v_lshl_add_u64 v[76:77], v[68:69], 0, s[6:7]
	v_lshl_add_u64 v[96:97], s[34:35], 0, v[80:81]
	s_mov_b64 s[18:19], 0
	v_mov_b32_e32 v89, v88
	v_mov_b32_e32 v90, v88
	v_mov_b32_e32 v91, v88
	v_mov_b32_e32 v80, v88
	v_mov_b32_e32 v81, v88
	v_mov_b32_e32 v82, v88
	v_mov_b32_e32 v83, v88
	v_mov_b32_e32 v84, v88
	v_mov_b32_e32 v85, v88
	v_mov_b32_e32 v86, v88
	v_mov_b32_e32 v87, v88
	v_mov_b32_e32 v92, v88
	v_mov_b32_e32 v93, v88
	v_mov_b32_e32 v94, v88
	v_mov_b32_e32 v95, v88
	v_mov_b32_e32 v98, v88
	v_mov_b32_e32 v99, v88
	v_mov_b32_e32 v100, v88
	v_mov_b32_e32 v101, v88
	v_mov_b32_e32 v102, v88
	v_mov_b32_e32 v103, v88
	v_mov_b32_e32 v104, v88
	v_mov_b32_e32 v105, v88
	v_mov_b32_e32 v106, v88
	v_mov_b32_e32 v107, v88
	v_mov_b32_e32 v108, v88
	v_mov_b32_e32 v109, v88
	v_mov_b32_e32 v110, v88
	v_mov_b32_e32 v111, v88
	v_mov_b32_e32 v112, v88
	v_mov_b32_e32 v113, v88
	v_subrev_u32_e32 v117, s34, v96
	v_add_u32_e32 v118, 0x1000, v117
	v_add_u32_e32 v119, 0x2000, v117
	s_add_u32 s100, s34, 0x415c8000
	s_addc_u32 s101, s35, 0
	global_load_dwordx4 v[120:123], v117, s[100:101] offset:1280
	global_load_dwordx4 v[124:127], v117, s[100:101] offset:2304
	global_load_dwordx4 v[128:131], v117, s[100:101] offset:3328
	global_load_dwordx4 v[132:135], v118, s[100:101] offset:256
	global_load_dwordx4 v[136:139], v118, s[100:101] offset:1280
	global_load_dwordx4 v[140:143], v118, s[100:101] offset:2304
	global_load_dwordx4 v[144:147], v118, s[100:101] offset:3328
	global_load_dwordx4 v[152:155], v119, s[100:101] offset:256
	s_add_u32 s100, s100, 0x20000
	s_addc_u32 s101, s101, 0
	global_load_dwordx4 v[156:159], v117, s[100:101] offset:1280
	global_load_dwordx4 v[160:163], v117, s[100:101] offset:2304
	global_load_dwordx4 v[164:167], v117, s[100:101] offset:3328
	global_load_dwordx4 v[168:171], v118, s[100:101] offset:256
	global_load_dwordx4 v[172:175], v118, s[100:101] offset:1280
	global_load_dwordx4 v[176:179], v118, s[100:101] offset:2304
	global_load_dwordx4 v[180:183], v118, s[100:101] offset:3328
	global_load_dwordx4 v[184:187], v119, s[100:101] offset:256
	s_add_u32 s100, s100, 0x20000
	s_addc_u32 s101, s101, 0
	global_load_dwordx4 v[188:191], v117, s[100:101] offset:1280
	global_load_dwordx4 v[192:195], v117, s[100:101] offset:2304
	global_load_dwordx4 v[196:199], v117, s[100:101] offset:3328
	global_load_dwordx4 v[200:203], v118, s[100:101] offset:256
	global_load_dwordx4 v[204:207], v118, s[100:101] offset:1280
	global_load_dwordx4 v[224:227], v118, s[100:101] offset:2304
	global_load_dwordx4 v[228:231], v118, s[100:101] offset:3328
	global_load_dwordx4 v[232:235], v119, s[100:101] offset:256
	s_add_u32 s100, s100, 0x20000
	s_addc_u32 s101, s101, 0
	s_waitcnt vmcnt(23)
; __device__ __forceinline__ void phase_resid(const Params& p, const float* g, bool first, bool last, int nsplit) {
;     ...
;         for (int sp = 0; sp < nsplit; ++sp) {
; #pragma unroll
;             for (int i = 0; i < 8; ++i) mv[i] += *(const f32x4*)(part + (size_t)(sp * 16 + gw) * DM + lane * 4 + 256 * i);
;         }
	v_pk_add_f32 v[110:111], v[110:111], v[120:121]
	v_pk_add_f32 v[112:113], v[112:113], v[122:123]
	global_load_dwordx4 v[120:123], v117, s[100:101] offset:1280
	s_waitcnt vmcnt(23)
	v_pk_add_f32 v[106:107], v[106:107], v[124:125]
	v_pk_add_f32 v[108:109], v[108:109], v[126:127]
	global_load_dwordx4 v[124:127], v117, s[100:101] offset:2304
	s_waitcnt vmcnt(23)
	v_pk_add_f32 v[102:103], v[102:103], v[128:129]
	v_pk_add_f32 v[104:105], v[104:105], v[130:131]
	global_load_dwordx4 v[128:131], v117, s[100:101] offset:3328
	s_waitcnt vmcnt(23)
	v_pk_add_f32 v[98:99], v[98:99], v[132:133]
	v_pk_add_f32 v[100:101], v[100:101], v[134:135]
	global_load_dwordx4 v[132:135], v118, s[100:101] offset:256
	s_waitcnt vmcnt(23)
	v_pk_add_f32 v[92:93], v[92:93], v[136:137]
	v_pk_add_f32 v[94:95], v[94:95], v[138:139]
	global_load_dwordx4 v[136:139], v118, s[100:101] offset:1280
	s_waitcnt vmcnt(23)
	v_pk_add_f32 v[84:85], v[84:85], v[140:141]
	v_pk_add_f32 v[86:87], v[86:87], v[142:143]
	global_load_dwordx4 v[140:143], v118, s[100:101] offset:2304
	s_waitcnt vmcnt(23)
	v_pk_add_f32 v[80:81], v[80:81], v[144:145]
	v_pk_add_f32 v[82:83], v[82:83], v[146:147]
	global_load_dwordx4 v[144:147], v118, s[100:101] offset:3328
	s_waitcnt vmcnt(23)
	v_pk_add_f32 v[88:89], v[88:89], v[152:153]
	v_pk_add_f32 v[90:91], v[90:91], v[154:155]
	global_load_dwordx4 v[152:155], v119, s[100:101] offset:256
	s_add_u32 s100, s100, 0x20000
	s_addc_u32 s101, s101, 0
	s_waitcnt vmcnt(23)
	v_pk_add_f32 v[110:111], v[110:111], v[156:157]
	v_pk_add_f32 v[112:113], v[112:113], v[158:159]
	global_load_dwordx4 v[156:159], v117, s[100:101] offset:1280
	s_waitcnt vmcnt(23)
	v_pk_add_f32 v[106:107], v[106:107], v[160:161]
	v_pk_add_f32 v[108:109], v[108:109], v[162:163]
	global_load_dwordx4 v[160:163], v117, s[100:101] offset:2304
	s_waitcnt vmcnt(23)
	v_pk_add_f32 v[102:103], v[102:103], v[164:165]
	v_pk_add_f32 v[104:105], v[104:105], v[166:167]
	global_load_dwordx4 v[164:167], v117, s[100:101] offset:3328
	s_waitcnt vmcnt(23)
	v_pk_add_f32 v[98:99], v[98:99], v[168:169]
	v_pk_add_f32 v[100:101], v[100:101], v[170:171]
	global_load_dwordx4 v[168:171], v118, s[100:101] offset:256
	s_waitcnt vmcnt(23)
	v_pk_add_f32 v[92:93], v[92:93], v[172:173]
	v_pk_add_f32 v[94:95], v[94:95], v[174:175]
	global_load_dwordx4 v[172:175], v118, s[100:101] offset:1280
	s_waitcnt vmcnt(23)
	v_pk_add_f32 v[84:85], v[84:85], v[176:177]
	v_pk_add_f32 v[86:87], v[86:87], v[178:179]
	global_load_dwordx4 v[176:179], v118, s[100:101] offset:2304
	s_waitcnt vmcnt(23)
	v_pk_add_f32 v[80:81], v[80:81], v[180:181]
	v_pk_add_f32 v[82:83], v[82:83], v[182:183]
	global_load_dwordx4 v[180:183], v118, s[100:101] offset:3328
	s_waitcnt vmcnt(23)
	v_pk_add_f32 v[88:89], v[88:89], v[184:185]
	v_pk_add_f32 v[90:91], v[90:91], v[186:187]
	global_load_dwordx4 v[184:187], v119, s[100:101] offset:256
	s_add_u32 s100, s100, 0x20000
	s_addc_u32 s101, s101, 0
	s_waitcnt vmcnt(23)
	v_pk_add_f32 v[110:111], v[110:111], v[188:189]
	v_pk_add_f32 v[112:113], v[112:113], v[190:191]
	global_load_dwordx4 v[188:191], v117, s[100:101] offset:1280
	s_waitcnt vmcnt(23)
	v_pk_add_f32 v[106:107], v[106:107], v[192:193]
	v_pk_add_f32 v[108:109], v[108:109], v[194:195]
	global_load_dwordx4 v[192:195], v117, s[100:101] offset:2304
	s_waitcnt vmcnt(23)
	v_pk_add_f32 v[102:103], v[102:103], v[196:197]
	v_pk_add_f32 v[104:105], v[104:105], v[198:199]
	global_load_dwordx4 v[196:199], v117, s[100:101] offset:3328
	s_waitcnt vmcnt(23)
	v_pk_add_f32 v[98:99], v[98:99], v[200:201]
	v_pk_add_f32 v[100:101], v[100:101], v[202:203]
	global_load_dwordx4 v[200:203], v118, s[100:101] offset:256
	s_waitcnt vmcnt(23)
	v_pk_add_f32 v[92:93], v[92:93], v[204:205]
	v_pk_add_f32 v[94:95], v[94:95], v[206:207]
	global_load_dwordx4 v[204:207], v118, s[100:101] offset:1280
	s_waitcnt vmcnt(23)
	v_pk_add_f32 v[84:85], v[84:85], v[224:225]
	v_pk_add_f32 v[86:87], v[86:87], v[226:227]
	global_load_dwordx4 v[224:227], v118, s[100:101] offset:2304
	s_waitcnt vmcnt(23)
	v_pk_add_f32 v[80:81], v[80:81], v[228:229]
	v_pk_add_f32 v[82:83], v[82:83], v[230:231]
	global_load_dwordx4 v[228:231], v118, s[100:101] offset:3328
	s_waitcnt vmcnt(23)
	v_pk_add_f32 v[88:89], v[88:89], v[232:233]
	v_pk_add_f32 v[90:91], v[90:91], v[234:235]
	global_load_dwordx4 v[232:235], v119, s[100:101] offset:256
	s_add_u32 s100, s100, 0x20000
	s_addc_u32 s101, s101, 0
	s_waitcnt vmcnt(23)
	v_pk_add_f32 v[110:111], v[110:111], v[120:121]
	v_pk_add_f32 v[112:113], v[112:113], v[122:123]
	global_load_dwordx4 v[120:123], v117, s[100:101] offset:1280
	s_waitcnt vmcnt(23)
	v_pk_add_f32 v[106:107], v[106:107], v[124:125]
	v_pk_add_f32 v[108:109], v[108:109], v[126:127]
	global_load_dwordx4 v[124:127], v117, s[100:101] offset:2304
	s_waitcnt vmcnt(23)
	v_pk_add_f32 v[102:103], v[102:103], v[128:129]
	v_pk_add_f32 v[104:105], v[104:105], v[130:131]
	global_load_dwordx4 v[128:131], v117, s[100:101] offset:3328
	s_waitcnt vmcnt(23)
	v_pk_add_f32 v[98:99], v[98:99], v[132:133]
	v_pk_add_f32 v[100:101], v[100:101], v[134:135]
	global_load_dwordx4 v[132:135], v118, s[100:101] offset:256
	s_waitcnt vmcnt(23)
	v_pk_add_f32 v[92:93], v[92:93], v[136:137]
	v_pk_add_f32 v[94:95], v[94:95], v[138:139]
	global_load_dwordx4 v[136:139], v118, s[100:101] offset:1280
	s_waitcnt vmcnt(23)
	v_pk_add_f32 v[84:85], v[84:85], v[140:141]
	v_pk_add_f32 v[86:87], v[86:87], v[142:143]
	global_load_dwordx4 v[140:143], v118, s[100:101] offset:2304
	s_waitcnt vmcnt(23)
	v_pk_add_f32 v[80:81], v[80:81], v[144:145]
	v_pk_add_f32 v[82:83], v[82:83], v[146:147]
	global_load_dwordx4 v[144:147], v118, s[100:101] offset:3328
	s_waitcnt vmcnt(23)
; __device__ __forceinline__ void phase_resid(const Params& p, const float* g, bool first, bool last, int nsplit) {
;     ...
;         for (int sp = 0; sp < nsplit; ++sp) {
; #pragma unroll
;             for (int i = 0; i < 8; ++i) mv[i] += *(const f32x4*)(part + (size_t)(sp * 16 + gw) * DM + lane * 4 + 256 * i);
;         }
	v_pk_add_f32 v[88:89], v[88:89], v[152:153]
	v_pk_add_f32 v[90:91], v[90:91], v[154:155]
	global_load_dwordx4 v[152:155], v119, s[100:101] offset:256
	s_add_u32 s100, s100, 0x20000
	s_addc_u32 s101, s101, 0
	s_waitcnt vmcnt(23)
	v_pk_add_f32 v[110:111], v[110:111], v[156:157]
	v_pk_add_f32 v[112:113], v[112:113], v[158:159]
	global_load_dwordx4 v[156:159], v117, s[100:101] offset:1280
	s_waitcnt vmcnt(23)
	v_pk_add_f32 v[106:107], v[106:107], v[160:161]
	v_pk_add_f32 v[108:109], v[108:109], v[162:163]
	global_load_dwordx4 v[160:163], v117, s[100:101] offset:2304
	s_waitcnt vmcnt(23)
	v_pk_add_f32 v[102:103], v[102:103], v[164:165]
	v_pk_add_f32 v[104:105], v[104:105], v[166:167]
	global_load_dwordx4 v[164:167], v117, s[100:101] offset:3328
	s_waitcnt vmcnt(23)
	v_pk_add_f32 v[98:99], v[98:99], v[168:169]
	v_pk_add_f32 v[100:101], v[100:101], v[170:171]
	global_load_dwordx4 v[168:171], v118, s[100:101] offset:256
	s_waitcnt vmcnt(23)
	v_pk_add_f32 v[92:93], v[92:93], v[172:173]
	v_pk_add_f32 v[94:95], v[94:95], v[174:175]
	global_load_dwordx4 v[172:175], v118, s[100:101] offset:1280
	s_waitcnt vmcnt(23)
	v_pk_add_f32 v[84:85], v[84:85], v[176:177]
	v_pk_add_f32 v[86:87], v[86:87], v[178:179]
	global_load_dwordx4 v[176:179], v118, s[100:101] offset:2304
	s_waitcnt vmcnt(23)
	v_pk_add_f32 v[80:81], v[80:81], v[180:181]
	v_pk_add_f32 v[82:83], v[82:83], v[182:183]
	global_load_dwordx4 v[180:183], v118, s[100:101] offset:3328
	s_waitcnt vmcnt(23)
	v_pk_add_f32 v[88:89], v[88:89], v[184:185]
	v_pk_add_f32 v[90:91], v[90:91], v[186:187]
	global_load_dwordx4 v[184:187], v119, s[100:101] offset:256
	s_add_u32 s100, s100, 0x20000
	s_addc_u32 s101, s101, 0
	s_waitcnt vmcnt(23)
	v_pk_add_f32 v[110:111], v[110:111], v[188:189]
	v_pk_add_f32 v[112:113], v[112:113], v[190:191]
	global_load_dwordx4 v[188:191], v117, s[100:101] offset:1280
	s_waitcnt vmcnt(23)
	v_pk_add_f32 v[106:107], v[106:107], v[192:193]
	v_pk_add_f32 v[108:109], v[108:109], v[194:195]
	global_load_dwordx4 v[192:195], v117, s[100:101] offset:2304
	s_waitcnt vmcnt(23)
	v_pk_add_f32 v[102:103], v[102:103], v[196:197]
	v_pk_add_f32 v[104:105], v[104:105], v[198:199]
	global_load_dwordx4 v[196:199], v117, s[100:101] offset:3328
	s_waitcnt vmcnt(23)
	v_pk_add_f32 v[98:99], v[98:99], v[200:201]
	v_pk_add_f32 v[100:101], v[100:101], v[202:203]
	global_load_dwordx4 v[200:203], v118, s[100:101] offset:256
	s_waitcnt vmcnt(23)
	v_pk_add_f32 v[92:93], v[92:93], v[204:205]
	v_pk_add_f32 v[94:95], v[94:95], v[206:207]
	global_load_dwordx4 v[204:207], v118, s[100:101] offset:1280
	s_waitcnt vmcnt(23)
	v_pk_add_f32 v[84:85], v[84:85], v[224:225]
	v_pk_add_f32 v[86:87], v[86:87], v[226:227]
	global_load_dwordx4 v[224:227], v118, s[100:101] offset:2304
	s_waitcnt vmcnt(23)
	v_pk_add_f32 v[80:81], v[80:81], v[228:229]
	v_pk_add_f32 v[82:83], v[82:83], v[230:231]
	global_load_dwordx4 v[228:231], v118, s[100:101] offset:3328
	s_waitcnt vmcnt(23)
	v_pk_add_f32 v[88:89], v[88:89], v[232:233]
	v_pk_add_f32 v[90:91], v[90:91], v[234:235]
	global_load_dwordx4 v[232:235], v119, s[100:101] offset:256
	s_add_u32 s100, s100, 0x20000
	s_addc_u32 s101, s101, 0
	s_waitcnt vmcnt(23)
	v_pk_add_f32 v[110:111], v[110:111], v[120:121]
	v_pk_add_f32 v[112:113], v[112:113], v[122:123]
	global_load_dwordx4 v[120:123], v117, s[100:101] offset:1280
	s_waitcnt vmcnt(23)
	v_pk_add_f32 v[106:107], v[106:107], v[124:125]
	v_pk_add_f32 v[108:109], v[108:109], v[126:127]
	global_load_dwordx4 v[124:127], v117, s[100:101] offset:2304
	s_waitcnt vmcnt(23)
	v_pk_add_f32 v[102:103], v[102:103], v[128:129]
	v_pk_add_f32 v[104:105], v[104:105], v[130:131]
	global_load_dwordx4 v[128:131], v117, s[100:101] offset:3328
	s_waitcnt vmcnt(23)
	v_pk_add_f32 v[98:99], v[98:99], v[132:133]
	v_pk_add_f32 v[100:101], v[100:101], v[134:135]
	global_load_dwordx4 v[132:135], v118, s[100:101] offset:256
	s_waitcnt vmcnt(23)
	v_pk_add_f32 v[92:93], v[92:93], v[136:137]
	v_pk_add_f32 v[94:95], v[94:95], v[138:139]
	global_load_dwordx4 v[136:139], v118, s[100:101] offset:1280
	s_waitcnt vmcnt(23)
	v_pk_add_f32 v[84:85], v[84:85], v[140:141]
	v_pk_add_f32 v[86:87], v[86:87], v[142:143]
	global_load_dwordx4 v[140:143], v118, s[100:101] offset:2304
	s_waitcnt vmcnt(23)
	v_pk_add_f32 v[80:81], v[80:81], v[144:145]
	v_pk_add_f32 v[82:83], v[82:83], v[146:147]
	global_load_dwordx4 v[144:147], v118, s[100:101] offset:3328
	s_waitcnt vmcnt(23)
	v_pk_add_f32 v[88:89], v[88:89], v[152:153]
	v_pk_add_f32 v[90:91], v[90:91], v[154:155]
	global_load_dwordx4 v[152:155], v119, s[100:101] offset:256
	s_add_u32 s100, s100, 0x20000
	s_addc_u32 s101, s101, 0
	s_waitcnt vmcnt(23)
	v_pk_add_f32 v[110:111], v[110:111], v[156:157]
	v_pk_add_f32 v[112:113], v[112:113], v[158:159]
	global_load_dwordx4 v[156:159], v117, s[100:101] offset:1280
	s_waitcnt vmcnt(23)
	v_pk_add_f32 v[106:107], v[106:107], v[160:161]
	v_pk_add_f32 v[108:109], v[108:109], v[162:163]
	global_load_dwordx4 v[160:163], v117, s[100:101] offset:2304
	s_waitcnt vmcnt(23)
	v_pk_add_f32 v[102:103], v[102:103], v[164:165]
	v_pk_add_f32 v[104:105], v[104:105], v[166:167]
	global_load_dwordx4 v[164:167], v117, s[100:101] offset:3328
	s_waitcnt vmcnt(23)
	v_pk_add_f32 v[98:99], v[98:99], v[168:169]
	v_pk_add_f32 v[100:101], v[100:101], v[170:171]
	global_load_dwordx4 v[168:171], v118, s[100:101] offset:256
	s_waitcnt vmcnt(23)
	v_pk_add_f32 v[92:93], v[92:93], v[172:173]
	v_pk_add_f32 v[94:95], v[94:95], v[174:175]
	global_load_dwordx4 v[172:175], v118, s[100:101] offset:1280
	s_waitcnt vmcnt(23)
	v_pk_add_f32 v[84:85], v[84:85], v[176:177]
	v_pk_add_f32 v[86:87], v[86:87], v[178:179]
	global_load_dwordx4 v[176:179], v118, s[100:101] offset:2304
	s_waitcnt vmcnt(23)
; __device__ __forceinline__ void phase_resid(const Params& p, const float* g, bool first, bool last, int nsplit) {
;     ...
;         for (int sp = 0; sp < nsplit; ++sp) {
; #pragma unroll
;             for (int i = 0; i < 8; ++i) mv[i] += *(const f32x4*)(part + (size_t)(sp * 16 + gw) * DM + lane * 4 + 256 * i);
;         }
	v_pk_add_f32 v[80:81], v[80:81], v[180:181]
	v_pk_add_f32 v[82:83], v[82:83], v[182:183]
	global_load_dwordx4 v[180:183], v118, s[100:101] offset:3328
	s_waitcnt vmcnt(23)
	v_pk_add_f32 v[88:89], v[88:89], v[184:185]
	v_pk_add_f32 v[90:91], v[90:91], v[186:187]
	global_load_dwordx4 v[184:187], v119, s[100:101] offset:256
	s_add_u32 s100, s100, 0x20000
	s_addc_u32 s101, s101, 0
	s_waitcnt vmcnt(23)
	v_pk_add_f32 v[110:111], v[110:111], v[188:189]
	v_pk_add_f32 v[112:113], v[112:113], v[190:191]
	global_load_dwordx4 v[188:191], v117, s[100:101] offset:1280
	s_waitcnt vmcnt(23)
	v_pk_add_f32 v[106:107], v[106:107], v[192:193]
	v_pk_add_f32 v[108:109], v[108:109], v[194:195]
	global_load_dwordx4 v[192:195], v117, s[100:101] offset:2304
	s_waitcnt vmcnt(23)
	v_pk_add_f32 v[102:103], v[102:103], v[196:197]
	v_pk_add_f32 v[104:105], v[104:105], v[198:199]
	global_load_dwordx4 v[196:199], v117, s[100:101] offset:3328
	s_waitcnt vmcnt(23)
	v_pk_add_f32 v[98:99], v[98:99], v[200:201]
	v_pk_add_f32 v[100:101], v[100:101], v[202:203]
	global_load_dwordx4 v[200:203], v118, s[100:101] offset:256
	s_waitcnt vmcnt(23)
	v_pk_add_f32 v[92:93], v[92:93], v[204:205]
	v_pk_add_f32 v[94:95], v[94:95], v[206:207]
	global_load_dwordx4 v[204:207], v118, s[100:101] offset:1280
	s_waitcnt vmcnt(23)
	v_pk_add_f32 v[84:85], v[84:85], v[224:225]
	v_pk_add_f32 v[86:87], v[86:87], v[226:227]
	global_load_dwordx4 v[224:227], v118, s[100:101] offset:2304
	s_waitcnt vmcnt(23)
	v_pk_add_f32 v[80:81], v[80:81], v[228:229]
	v_pk_add_f32 v[82:83], v[82:83], v[230:231]
	global_load_dwordx4 v[228:231], v118, s[100:101] offset:3328
	s_waitcnt vmcnt(23)
	v_pk_add_f32 v[88:89], v[88:89], v[232:233]
	v_pk_add_f32 v[90:91], v[90:91], v[234:235]
	global_load_dwordx4 v[232:235], v119, s[100:101] offset:256
	s_add_u32 s100, s100, 0x20000
	s_addc_u32 s101, s101, 0
	s_waitcnt vmcnt(23)
	v_pk_add_f32 v[110:111], v[110:111], v[120:121]
	v_pk_add_f32 v[112:113], v[112:113], v[122:123]
	global_load_dwordx4 v[120:123], v117, s[100:101] offset:1280
	s_waitcnt vmcnt(23)
	v_pk_add_f32 v[106:107], v[106:107], v[124:125]
	v_pk_add_f32 v[108:109], v[108:109], v[126:127]
	global_load_dwordx4 v[124:127], v117, s[100:101] offset:2304
	s_waitcnt vmcnt(23)
	v_pk_add_f32 v[102:103], v[102:103], v[128:129]
	v_pk_add_f32 v[104:105], v[104:105], v[130:131]
	global_load_dwordx4 v[128:131], v117, s[100:101] offset:3328
	s_waitcnt vmcnt(23)
	v_pk_add_f32 v[98:99], v[98:99], v[132:133]
	v_pk_add_f32 v[100:101], v[100:101], v[134:135]
	global_load_dwordx4 v[132:135], v118, s[100:101] offset:256
	s_waitcnt vmcnt(23)
	v_pk_add_f32 v[92:93], v[92:93], v[136:137]
	v_pk_add_f32 v[94:95], v[94:95], v[138:139]
	global_load_dwordx4 v[136:139], v118, s[100:101] offset:1280
	s_waitcnt vmcnt(23)
	v_pk_add_f32 v[84:85], v[84:85], v[140:141]
	v_pk_add_f32 v[86:87], v[86:87], v[142:143]
	global_load_dwordx4 v[140:143], v118, s[100:101] offset:2304
	s_waitcnt vmcnt(23)
	v_pk_add_f32 v[80:81], v[80:81], v[144:145]
	v_pk_add_f32 v[82:83], v[82:83], v[146:147]
	global_load_dwordx4 v[144:147], v118, s[100:101] offset:3328
	s_waitcnt vmcnt(23)
	v_pk_add_f32 v[88:89], v[88:89], v[152:153]
	v_pk_add_f32 v[90:91], v[90:91], v[154:155]
	global_load_dwordx4 v[152:155], v119, s[100:101] offset:256
	s_add_u32 s100, s100, 0x20000
	s_addc_u32 s101, s101, 0
	s_waitcnt vmcnt(23)
	v_pk_add_f32 v[110:111], v[110:111], v[156:157]
	v_pk_add_f32 v[112:113], v[112:113], v[158:159]
	global_load_dwordx4 v[156:159], v117, s[100:101] offset:1280
	s_waitcnt vmcnt(23)
	v_pk_add_f32 v[106:107], v[106:107], v[160:161]
	v_pk_add_f32 v[108:109], v[108:109], v[162:163]
	global_load_dwordx4 v[160:163], v117, s[100:101] offset:2304
	s_waitcnt vmcnt(23)
	v_pk_add_f32 v[102:103], v[102:103], v[164:165]
	v_pk_add_f32 v[104:105], v[104:105], v[166:167]
	global_load_dwordx4 v[164:167], v117, s[100:101] offset:3328
	s_waitcnt vmcnt(23)
	v_pk_add_f32 v[98:99], v[98:99], v[168:169]
	v_pk_add_f32 v[100:101], v[100:101], v[170:171]
	global_load_dwordx4 v[168:171], v118, s[100:101] offset:256
	s_waitcnt vmcnt(23)
	v_pk_add_f32 v[92:93], v[92:93], v[172:173]
	v_pk_add_f32 v[94:95], v[94:95], v[174:175]
	global_load_dwordx4 v[172:175], v118, s[100:101] offset:1280
	s_waitcnt vmcnt(23)
	v_pk_add_f32 v[84:85], v[84:85], v[176:177]
	v_pk_add_f32 v[86:87], v[86:87], v[178:179]
	global_load_dwordx4 v[176:179], v118, s[100:101] offset:2304
	s_waitcnt vmcnt(23)
	v_pk_add_f32 v[80:81], v[80:81], v[180:181]
	v_pk_add_f32 v[82:83], v[82:83], v[182:183]
	global_load_dwordx4 v[180:183], v118, s[100:101] offset:3328
	s_waitcnt vmcnt(23)
	v_pk_add_f32 v[88:89], v[88:89], v[184:185]
	v_pk_add_f32 v[90:91], v[90:91], v[186:187]
	global_load_dwordx4 v[184:187], v119, s[100:101] offset:256
	s_add_u32 s100, s100, 0x20000
	s_addc_u32 s101, s101, 0
	s_waitcnt vmcnt(23)
	v_pk_add_f32 v[110:111], v[110:111], v[188:189]
	v_pk_add_f32 v[112:113], v[112:113], v[190:191]
	global_load_dwordx4 v[188:191], v117, s[100:101] offset:1280
	s_waitcnt vmcnt(23)
	v_pk_add_f32 v[106:107], v[106:107], v[192:193]
	v_pk_add_f32 v[108:109], v[108:109], v[194:195]
	global_load_dwordx4 v[192:195], v117, s[100:101] offset:2304
	s_waitcnt vmcnt(23)
	v_pk_add_f32 v[102:103], v[102:103], v[196:197]
	v_pk_add_f32 v[104:105], v[104:105], v[198:199]
	global_load_dwordx4 v[196:199], v117, s[100:101] offset:3328
	s_waitcnt vmcnt(23)
	v_pk_add_f32 v[98:99], v[98:99], v[200:201]
	v_pk_add_f32 v[100:101], v[100:101], v[202:203]
	global_load_dwordx4 v[200:203], v118, s[100:101] offset:256
	s_waitcnt vmcnt(23)
	v_pk_add_f32 v[92:93], v[92:93], v[204:205]
	v_pk_add_f32 v[94:95], v[94:95], v[206:207]
	global_load_dwordx4 v[204:207], v118, s[100:101] offset:1280
	s_waitcnt vmcnt(23)
; __device__ __forceinline__ void phase_resid(const Params& p, const float* g, bool first, bool last, int nsplit) {
;     ...
;         for (int sp = 0; sp < nsplit; ++sp) {
; #pragma unroll
;             for (int i = 0; i < 8; ++i) mv[i] += *(const f32x4*)(part + (size_t)(sp * 16 + gw) * DM + lane * 4 + 256 * i);
;         }
	v_pk_add_f32 v[84:85], v[84:85], v[224:225]
	v_pk_add_f32 v[86:87], v[86:87], v[226:227]
	global_load_dwordx4 v[224:227], v118, s[100:101] offset:2304
	s_waitcnt vmcnt(23)
	v_pk_add_f32 v[80:81], v[80:81], v[228:229]
	v_pk_add_f32 v[82:83], v[82:83], v[230:231]
	global_load_dwordx4 v[228:231], v118, s[100:101] offset:3328
	s_waitcnt vmcnt(23)
	v_pk_add_f32 v[88:89], v[88:89], v[232:233]
	v_pk_add_f32 v[90:91], v[90:91], v[234:235]
	global_load_dwordx4 v[232:235], v119, s[100:101] offset:256
	s_add_u32 s100, s100, 0x20000
	s_addc_u32 s101, s101, 0
	s_waitcnt vmcnt(23)
	v_pk_add_f32 v[110:111], v[110:111], v[120:121]
	v_pk_add_f32 v[112:113], v[112:113], v[122:123]
	global_load_dwordx4 v[120:123], v117, s[100:101] offset:1280
	s_waitcnt vmcnt(23)
	v_pk_add_f32 v[106:107], v[106:107], v[124:125]
	v_pk_add_f32 v[108:109], v[108:109], v[126:127]
	global_load_dwordx4 v[124:127], v117, s[100:101] offset:2304
	s_waitcnt vmcnt(23)
	v_pk_add_f32 v[102:103], v[102:103], v[128:129]
	v_pk_add_f32 v[104:105], v[104:105], v[130:131]
	global_load_dwordx4 v[128:131], v117, s[100:101] offset:3328
	s_waitcnt vmcnt(23)
	v_pk_add_f32 v[98:99], v[98:99], v[132:133]
	v_pk_add_f32 v[100:101], v[100:101], v[134:135]
	global_load_dwordx4 v[132:135], v118, s[100:101] offset:256
	s_waitcnt vmcnt(23)
	v_pk_add_f32 v[92:93], v[92:93], v[136:137]
	v_pk_add_f32 v[94:95], v[94:95], v[138:139]
	global_load_dwordx4 v[136:139], v118, s[100:101] offset:1280
	s_waitcnt vmcnt(23)
	v_pk_add_f32 v[84:85], v[84:85], v[140:141]
	v_pk_add_f32 v[86:87], v[86:87], v[142:143]
	global_load_dwordx4 v[140:143], v118, s[100:101] offset:2304
	s_waitcnt vmcnt(23)
	v_pk_add_f32 v[80:81], v[80:81], v[144:145]
	v_pk_add_f32 v[82:83], v[82:83], v[146:147]
	global_load_dwordx4 v[144:147], v118, s[100:101] offset:3328
	s_waitcnt vmcnt(23)
	v_pk_add_f32 v[88:89], v[88:89], v[152:153]
	v_pk_add_f32 v[90:91], v[90:91], v[154:155]
	global_load_dwordx4 v[152:155], v119, s[100:101] offset:256
	s_add_u32 s100, s100, 0x20000
	s_addc_u32 s101, s101, 0
	s_waitcnt vmcnt(23)
	v_pk_add_f32 v[110:111], v[110:111], v[156:157]
	v_pk_add_f32 v[112:113], v[112:113], v[158:159]
	global_load_dwordx4 v[156:159], v117, s[100:101] offset:1280
	s_waitcnt vmcnt(23)
	v_pk_add_f32 v[106:107], v[106:107], v[160:161]
	v_pk_add_f32 v[108:109], v[108:109], v[162:163]
	global_load_dwordx4 v[160:163], v117, s[100:101] offset:2304
	s_waitcnt vmcnt(23)
	v_pk_add_f32 v[102:103], v[102:103], v[164:165]
	v_pk_add_f32 v[104:105], v[104:105], v[166:167]
	global_load_dwordx4 v[164:167], v117, s[100:101] offset:3328
	s_waitcnt vmcnt(23)
	v_pk_add_f32 v[98:99], v[98:99], v[168:169]
	v_pk_add_f32 v[100:101], v[100:101], v[170:171]
	global_load_dwordx4 v[168:171], v118, s[100:101] offset:256
	s_waitcnt vmcnt(23)
	v_pk_add_f32 v[92:93], v[92:93], v[172:173]
	v_pk_add_f32 v[94:95], v[94:95], v[174:175]
	global_load_dwordx4 v[172:175], v118, s[100:101] offset:1280
	s_waitcnt vmcnt(23)
	v_pk_add_f32 v[84:85], v[84:85], v[176:177]
	v_pk_add_f32 v[86:87], v[86:87], v[178:179]
	global_load_dwordx4 v[176:179], v118, s[100:101] offset:2304
	s_waitcnt vmcnt(23)
	v_pk_add_f32 v[80:81], v[80:81], v[180:181]
	v_pk_add_f32 v[82:83], v[82:83], v[182:183]
	global_load_dwordx4 v[180:183], v118, s[100:101] offset:3328
	s_waitcnt vmcnt(23)
	v_pk_add_f32 v[88:89], v[88:89], v[184:185]
	v_pk_add_f32 v[90:91], v[90:91], v[186:187]
	global_load_dwordx4 v[184:187], v119, s[100:101] offset:256
	s_add_u32 s100, s100, 0x20000
	s_addc_u32 s101, s101, 0
	s_waitcnt vmcnt(23)
	v_pk_add_f32 v[110:111], v[110:111], v[188:189]
	v_pk_add_f32 v[112:113], v[112:113], v[190:191]
	global_load_dwordx4 v[188:191], v117, s[100:101] offset:1280
	s_waitcnt vmcnt(23)
	v_pk_add_f32 v[106:107], v[106:107], v[192:193]
	v_pk_add_f32 v[108:109], v[108:109], v[194:195]
	global_load_dwordx4 v[192:195], v117, s[100:101] offset:2304
	s_waitcnt vmcnt(23)
	v_pk_add_f32 v[102:103], v[102:103], v[196:197]
	v_pk_add_f32 v[104:105], v[104:105], v[198:199]
	global_load_dwordx4 v[196:199], v117, s[100:101] offset:3328
	s_waitcnt vmcnt(23)
	v_pk_add_f32 v[98:99], v[98:99], v[200:201]
	v_pk_add_f32 v[100:101], v[100:101], v[202:203]
	global_load_dwordx4 v[200:203], v118, s[100:101] offset:256
	s_waitcnt vmcnt(23)
	v_pk_add_f32 v[92:93], v[92:93], v[204:205]
	v_pk_add_f32 v[94:95], v[94:95], v[206:207]
	global_load_dwordx4 v[204:207], v118, s[100:101] offset:1280
	s_waitcnt vmcnt(23)
	v_pk_add_f32 v[84:85], v[84:85], v[224:225]
	v_pk_add_f32 v[86:87], v[86:87], v[226:227]
	global_load_dwordx4 v[224:227], v118, s[100:101] offset:2304
	s_waitcnt vmcnt(23)
	v_pk_add_f32 v[80:81], v[80:81], v[228:229]
	v_pk_add_f32 v[82:83], v[82:83], v[230:231]
	global_load_dwordx4 v[228:231], v118, s[100:101] offset:3328
	s_waitcnt vmcnt(23)
	v_pk_add_f32 v[88:89], v[88:89], v[232:233]
	v_pk_add_f32 v[90:91], v[90:91], v[234:235]
	global_load_dwordx4 v[232:235], v119, s[100:101] offset:256
	s_add_u32 s100, s100, 0x20000
	s_addc_u32 s101, s101, 0
	s_waitcnt vmcnt(23)
	v_pk_add_f32 v[110:111], v[110:111], v[120:121]
	v_pk_add_f32 v[112:113], v[112:113], v[122:123]
	global_load_dwordx4 v[120:123], v117, s[100:101] offset:1280
	s_waitcnt vmcnt(23)
	v_pk_add_f32 v[106:107], v[106:107], v[124:125]
	v_pk_add_f32 v[108:109], v[108:109], v[126:127]
	global_load_dwordx4 v[124:127], v117, s[100:101] offset:2304
	s_waitcnt vmcnt(23)
	v_pk_add_f32 v[102:103], v[102:103], v[128:129]
	v_pk_add_f32 v[104:105], v[104:105], v[130:131]
	global_load_dwordx4 v[128:131], v117, s[100:101] offset:3328
	s_waitcnt vmcnt(23)
	v_pk_add_f32 v[98:99], v[98:99], v[132:133]
	v_pk_add_f32 v[100:101], v[100:101], v[134:135]
	global_load_dwordx4 v[132:135], v118, s[100:101] offset:256
	s_waitcnt vmcnt(23)
; __device__ __forceinline__ void phase_resid(const Params& p, const float* g, bool first, bool last, int nsplit) {
;     ...
;         for (int sp = 0; sp < nsplit; ++sp) {
; #pragma unroll
;             for (int i = 0; i < 8; ++i) mv[i] += *(const f32x4*)(part + (size_t)(sp * 16 + gw) * DM + lane * 4 + 256 * i);
;         }
	v_pk_add_f32 v[92:93], v[92:93], v[136:137]
	v_pk_add_f32 v[94:95], v[94:95], v[138:139]
	global_load_dwordx4 v[136:139], v118, s[100:101] offset:1280
	s_waitcnt vmcnt(23)
	v_pk_add_f32 v[84:85], v[84:85], v[140:141]
	v_pk_add_f32 v[86:87], v[86:87], v[142:143]
	global_load_dwordx4 v[140:143], v118, s[100:101] offset:2304
	s_waitcnt vmcnt(23)
	v_pk_add_f32 v[80:81], v[80:81], v[144:145]
	v_pk_add_f32 v[82:83], v[82:83], v[146:147]
	global_load_dwordx4 v[144:147], v118, s[100:101] offset:3328
	s_waitcnt vmcnt(23)
	v_pk_add_f32 v[88:89], v[88:89], v[152:153]
	v_pk_add_f32 v[90:91], v[90:91], v[154:155]
	global_load_dwordx4 v[152:155], v119, s[100:101] offset:256
	s_add_u32 s100, s100, 0x20000
	s_addc_u32 s101, s101, 0
	s_waitcnt vmcnt(23)
	v_pk_add_f32 v[110:111], v[110:111], v[156:157]
	v_pk_add_f32 v[112:113], v[112:113], v[158:159]
	global_load_dwordx4 v[156:159], v117, s[100:101] offset:1280
	s_waitcnt vmcnt(23)
	v_pk_add_f32 v[106:107], v[106:107], v[160:161]
	v_pk_add_f32 v[108:109], v[108:109], v[162:163]
	global_load_dwordx4 v[160:163], v117, s[100:101] offset:2304
	s_waitcnt vmcnt(23)
	v_pk_add_f32 v[102:103], v[102:103], v[164:165]
	v_pk_add_f32 v[104:105], v[104:105], v[166:167]
	global_load_dwordx4 v[164:167], v117, s[100:101] offset:3328
	s_waitcnt vmcnt(23)
	v_pk_add_f32 v[98:99], v[98:99], v[168:169]
	v_pk_add_f32 v[100:101], v[100:101], v[170:171]
	global_load_dwordx4 v[168:171], v118, s[100:101] offset:256
	s_waitcnt vmcnt(23)
	v_pk_add_f32 v[92:93], v[92:93], v[172:173]
	v_pk_add_f32 v[94:95], v[94:95], v[174:175]
	global_load_dwordx4 v[172:175], v118, s[100:101] offset:1280
	s_waitcnt vmcnt(23)
	v_pk_add_f32 v[84:85], v[84:85], v[176:177]
	v_pk_add_f32 v[86:87], v[86:87], v[178:179]
	global_load_dwordx4 v[176:179], v118, s[100:101] offset:2304
	s_waitcnt vmcnt(23)
	v_pk_add_f32 v[80:81], v[80:81], v[180:181]
	v_pk_add_f32 v[82:83], v[82:83], v[182:183]
	global_load_dwordx4 v[180:183], v118, s[100:101] offset:3328
	s_waitcnt vmcnt(23)
	v_pk_add_f32 v[88:89], v[88:89], v[184:185]
	v_pk_add_f32 v[90:91], v[90:91], v[186:187]
	global_load_dwordx4 v[184:187], v119, s[100:101] offset:256
	s_add_u32 s100, s100, 0x20000
	s_addc_u32 s101, s101, 0
	s_waitcnt vmcnt(23)
	v_pk_add_f32 v[110:111], v[110:111], v[188:189]
	v_pk_add_f32 v[112:113], v[112:113], v[190:191]
	global_load_dwordx4 v[188:191], v117, s[100:101] offset:1280
	s_waitcnt vmcnt(23)
	v_pk_add_f32 v[106:107], v[106:107], v[192:193]
	v_pk_add_f32 v[108:109], v[108:109], v[194:195]
	global_load_dwordx4 v[192:195], v117, s[100:101] offset:2304
	s_waitcnt vmcnt(23)
	v_pk_add_f32 v[102:103], v[102:103], v[196:197]
	v_pk_add_f32 v[104:105], v[104:105], v[198:199]
	global_load_dwordx4 v[196:199], v117, s[100:101] offset:3328
	s_waitcnt vmcnt(23)
	v_pk_add_f32 v[98:99], v[98:99], v[200:201]
	v_pk_add_f32 v[100:101], v[100:101], v[202:203]
	global_load_dwordx4 v[200:203], v118, s[100:101] offset:256
	s_waitcnt vmcnt(23)
	v_pk_add_f32 v[92:93], v[92:93], v[204:205]
	v_pk_add_f32 v[94:95], v[94:95], v[206:207]
	global_load_dwordx4 v[204:207], v118, s[100:101] offset:1280
	s_waitcnt vmcnt(23)
	v_pk_add_f32 v[84:85], v[84:85], v[224:225]
	v_pk_add_f32 v[86:87], v[86:87], v[226:227]
	global_load_dwordx4 v[224:227], v118, s[100:101] offset:2304
	s_waitcnt vmcnt(23)
	v_pk_add_f32 v[80:81], v[80:81], v[228:229]
	v_pk_add_f32 v[82:83], v[82:83], v[230:231]
	global_load_dwordx4 v[228:231], v118, s[100:101] offset:3328
	s_waitcnt vmcnt(23)
	v_pk_add_f32 v[88:89], v[88:89], v[232:233]
	v_pk_add_f32 v[90:91], v[90:91], v[234:235]
	global_load_dwordx4 v[232:235], v119, s[100:101] offset:256
	s_add_u32 s100, s100, 0x20000
	s_addc_u32 s101, s101, 0
	s_waitcnt vmcnt(23)
	v_pk_add_f32 v[110:111], v[110:111], v[120:121]
	v_pk_add_f32 v[112:113], v[112:113], v[122:123]
	global_load_dwordx4 v[120:123], v117, s[100:101] offset:1280
	s_waitcnt vmcnt(23)
	v_pk_add_f32 v[106:107], v[106:107], v[124:125]
	v_pk_add_f32 v[108:109], v[108:109], v[126:127]
	global_load_dwordx4 v[124:127], v117, s[100:101] offset:2304
	s_waitcnt vmcnt(23)
	v_pk_add_f32 v[102:103], v[102:103], v[128:129]
	v_pk_add_f32 v[104:105], v[104:105], v[130:131]
	global_load_dwordx4 v[128:131], v117, s[100:101] offset:3328
	s_waitcnt vmcnt(23)
	v_pk_add_f32 v[98:99], v[98:99], v[132:133]
	v_pk_add_f32 v[100:101], v[100:101], v[134:135]
	global_load_dwordx4 v[132:135], v118, s[100:101] offset:256
	s_waitcnt vmcnt(23)
	v_pk_add_f32 v[92:93], v[92:93], v[136:137]
	v_pk_add_f32 v[94:95], v[94:95], v[138:139]
	global_load_dwordx4 v[136:139], v118, s[100:101] offset:1280
	s_waitcnt vmcnt(23)
	v_pk_add_f32 v[84:85], v[84:85], v[140:141]
	v_pk_add_f32 v[86:87], v[86:87], v[142:143]
	global_load_dwordx4 v[140:143], v118, s[100:101] offset:2304
	s_waitcnt vmcnt(23)
	v_pk_add_f32 v[80:81], v[80:81], v[144:145]
	v_pk_add_f32 v[82:83], v[82:83], v[146:147]
	global_load_dwordx4 v[144:147], v118, s[100:101] offset:3328
	s_waitcnt vmcnt(23)
	v_pk_add_f32 v[88:89], v[88:89], v[152:153]
	v_pk_add_f32 v[90:91], v[90:91], v[154:155]
	global_load_dwordx4 v[152:155], v119, s[100:101] offset:256
	s_waitcnt vmcnt(23)
	v_pk_add_f32 v[110:111], v[110:111], v[156:157]
	v_pk_add_f32 v[112:113], v[112:113], v[158:159]
	s_waitcnt vmcnt(22)
	v_pk_add_f32 v[106:107], v[106:107], v[160:161]
	v_pk_add_f32 v[108:109], v[108:109], v[162:163]
	s_waitcnt vmcnt(21)
	v_pk_add_f32 v[102:103], v[102:103], v[164:165]
	v_pk_add_f32 v[104:105], v[104:105], v[166:167]
	s_waitcnt vmcnt(20)
	v_pk_add_f32 v[98:99], v[98:99], v[168:169]
	v_pk_add_f32 v[100:101], v[100:101], v[170:171]
	s_waitcnt vmcnt(19)
	v_pk_add_f32 v[92:93], v[92:93], v[172:173]
	v_pk_add_f32 v[94:95], v[94:95], v[174:175]
	s_waitcnt vmcnt(18)
; __device__ __forceinline__ void phase_resid(const Params& p, const float* g, bool first, bool last, int nsplit) {
;     ...
;         for (int sp = 0; sp < nsplit; ++sp) {
; #pragma unroll
;             for (int i = 0; i < 8; ++i) mv[i] += *(const f32x4*)(part + (size_t)(sp * 16 + gw) * DM + lane * 4 + 256 * i);
;         }
	v_pk_add_f32 v[84:85], v[84:85], v[176:177]
	v_pk_add_f32 v[86:87], v[86:87], v[178:179]
	s_waitcnt vmcnt(17)
	v_pk_add_f32 v[80:81], v[80:81], v[180:181]
	v_pk_add_f32 v[82:83], v[82:83], v[182:183]
	s_waitcnt vmcnt(16)
	v_pk_add_f32 v[88:89], v[88:89], v[184:185]
	v_pk_add_f32 v[90:91], v[90:91], v[186:187]
	s_waitcnt vmcnt(15)
	v_pk_add_f32 v[110:111], v[110:111], v[188:189]
	v_pk_add_f32 v[112:113], v[112:113], v[190:191]
	s_waitcnt vmcnt(14)
	v_pk_add_f32 v[106:107], v[106:107], v[192:193]
	v_pk_add_f32 v[108:109], v[108:109], v[194:195]
	s_waitcnt vmcnt(13)
	v_pk_add_f32 v[102:103], v[102:103], v[196:197]
	v_pk_add_f32 v[104:105], v[104:105], v[198:199]
	s_waitcnt vmcnt(12)
	v_pk_add_f32 v[98:99], v[98:99], v[200:201]
	v_pk_add_f32 v[100:101], v[100:101], v[202:203]
	s_waitcnt vmcnt(11)
	v_pk_add_f32 v[92:93], v[92:93], v[204:205]
	v_pk_add_f32 v[94:95], v[94:95], v[206:207]
	s_waitcnt vmcnt(10)
	v_pk_add_f32 v[84:85], v[84:85], v[224:225]
	v_pk_add_f32 v[86:87], v[86:87], v[226:227]
	s_waitcnt vmcnt(9)
	v_pk_add_f32 v[80:81], v[80:81], v[228:229]
	v_pk_add_f32 v[82:83], v[82:83], v[230:231]
	s_waitcnt vmcnt(8)
	v_pk_add_f32 v[88:89], v[88:89], v[232:233]
	v_pk_add_f32 v[90:91], v[90:91], v[234:235]
	s_waitcnt vmcnt(7)
	v_pk_add_f32 v[110:111], v[110:111], v[120:121]
	v_pk_add_f32 v[112:113], v[112:113], v[122:123]
	s_waitcnt vmcnt(6)
	v_pk_add_f32 v[106:107], v[106:107], v[124:125]
	v_pk_add_f32 v[108:109], v[108:109], v[126:127]
	s_waitcnt vmcnt(5)
	v_pk_add_f32 v[102:103], v[102:103], v[128:129]
	v_pk_add_f32 v[104:105], v[104:105], v[130:131]
	s_waitcnt vmcnt(4)
	v_pk_add_f32 v[98:99], v[98:99], v[132:133]
	v_pk_add_f32 v[100:101], v[100:101], v[134:135]
	s_waitcnt vmcnt(3)
	v_pk_add_f32 v[92:93], v[92:93], v[136:137]
	v_pk_add_f32 v[94:95], v[94:95], v[138:139]
	s_waitcnt vmcnt(2)
	v_pk_add_f32 v[84:85], v[84:85], v[140:141]
	v_pk_add_f32 v[86:87], v[86:87], v[142:143]
	s_waitcnt vmcnt(1)
	v_pk_add_f32 v[80:81], v[80:81], v[144:145]
	v_pk_add_f32 v[82:83], v[82:83], v[146:147]
	s_waitcnt vmcnt(0) lgkmcnt(0)
	v_pk_add_f32 v[88:89], v[88:89], v[152:153]
	v_pk_add_f32 v[90:91], v[90:91], v[154:155]
	s_mov_b32 s18, 0x2c0000
	v_mul_f32_e32 v67, v111, v111
	v_mul_f32_e32 v71, v107, v107
	v_fmac_f32_e32 v67, v110, v110
	v_fmac_f32_e32 v71, v106, v106
	v_fmac_f32_e32 v67, v112, v112
	v_fmac_f32_e32 v71, v108, v108
	v_fmac_f32_e32 v67, v113, v113
	v_fmac_f32_e32 v71, v109, v109
	v_add_f32_e32 v67, v67, v71
	v_mul_f32_e32 v71, v103, v103
	v_fmac_f32_e32 v71, v102, v102
	v_fmac_f32_e32 v71, v104, v104
	v_fmac_f32_e32 v71, v105, v105
	v_add_f32_e32 v67, v67, v71
	v_mul_f32_e32 v71, v99, v99
	v_mov_b32_e32 v114, v93
	v_mov_b32_e32 v115, v85
	v_fmac_f32_e32 v71, v98, v98
	v_mov_b32_e32 v96, v92
	v_mov_b32_e32 v97, v84
	v_pk_mul_f32 v[114:115], v[114:115], v[114:115]
	v_fmac_f32_e32 v71, v100, v100
	v_pk_fma_f32 v[96:97], v[96:97], v[96:97], v[114:115]
	v_mov_b32_e32 v114, v94
	v_mov_b32_e32 v115, v86
	v_fmac_f32_e32 v71, v101, v101
	v_pk_fma_f32 v[96:97], v[114:115], v[114:115], v[96:97]
	v_mov_b32_e32 v114, v95
	v_mov_b32_e32 v115, v87
	v_add_f32_e32 v67, v67, v71
	v_pk_fma_f32 v[96:97], v[114:115], v[114:115], v[96:97]
	v_mov_b32_e32 v114, v81
	v_add_f32_e32 v67, v67, v96
	v_mov_b32_e32 v115, v89
	v_add_f32_e32 v67, v67, v97
	v_mov_b32_e32 v96, v80
	v_mov_b32_e32 v97, v88
	v_pk_mul_f32 v[114:115], v[114:115], v[114:115]
	s_nop 0
	v_pk_fma_f32 v[96:97], v[96:97], v[96:97], v[114:115]
	v_mov_b32_e32 v114, v82
	v_mov_b32_e32 v115, v90
	v_pk_fma_f32 v[96:97], v[114:115], v[114:115], v[96:97]
	v_mov_b32_e32 v114, v83
	v_mov_b32_e32 v115, v91
	v_pk_fma_f32 v[96:97], v[114:115], v[114:115], v[96:97]
	s_nop 0
	v_add_f32_e32 v67, v67, v96
	v_add_f32_e32 v71, v67, v97
	v_and_b32_e32 v67, 64, v215
	v_add_u32_e32 v115, 64, v67
	v_xor_b32_e32 v67, 32, v215
	v_cmp_lt_i32_e32 vcc, v67, v115
	s_nop 1
	v_cndmask_b32_e32 v67, v215, v67, vcc
	v_lshlrev_b32_e32 v67, 2, v67
	ds_bpermute_b32 v96, v67, v71
	s_waitcnt lgkmcnt(0)
	v_add_f32_e32 v96, v71, v96
	v_xor_b32_e32 v71, 16, v215
	v_cmp_lt_i32_e32 vcc, v71, v115
	s_nop 1
	v_cndmask_b32_e32 v71, v215, v71, vcc
	v_lshlrev_b32_e32 v71, 2, v71
	ds_bpermute_b32 v97, v71, v96
	s_waitcnt lgkmcnt(0)
	v_add_f32_e32 v97, v96, v97
	v_xor_b32_e32 v96, 8, v215
	v_cmp_lt_i32_e32 vcc, v96, v115
	s_nop 1
	v_cndmask_b32_e32 v96, v215, v96, vcc
	v_lshlrev_b32_e32 v96, 2, v96
	ds_bpermute_b32 v114, v96, v97
	s_waitcnt lgkmcnt(0)
	v_add_f32_e32 v114, v97, v114
	v_xor_b32_e32 v97, 4, v215
	v_cmp_lt_i32_e32 vcc, v97, v115
	s_nop 1
	v_cndmask_b32_e32 v97, v215, v97, vcc
	v_lshlrev_b32_e32 v97, 2, v97
	ds_bpermute_b32 v117, v97, v114
	s_waitcnt lgkmcnt(0)
	v_add_f32_e32 v117, v114, v117
	v_xor_b32_e32 v114, 2, v215
	v_cmp_lt_i32_e32 vcc, v114, v115
	s_nop 1
	v_cndmask_b32_e32 v114, v215, v114, vcc
	v_lshlrev_b32_e32 v114, 2, v114
	ds_bpermute_b32 v118, v114, v117
	s_waitcnt lgkmcnt(0)
	v_add_f32_e32 v117, v117, v118
	v_xor_b32_e32 v118, 1, v215
	v_cmp_lt_i32_e32 vcc, v118, v115
	s_nop 1
	v_cndmask_b32_e32 v115, v215, v118, vcc
	v_lshlrev_b32_e32 v115, 2, v115
	ds_bpermute_b32 v118, v115, v117
	s_andn2_b64 vcc, exec, s[8:9]
	s_cbranch_vccnz .LBB0_308
	s_waitcnt lgkmcnt(0)
	v_add_f32_e32 v117, v117, v118
	v_fmamk_f32 v117, v117, 0x3a000000, v212
	s_mov_b32 s3, 0x800000
	v_mul_f32_e32 v118, 0x4b800000, v117
	v_cmp_gt_f32_e32 vcc, s3, v117
	v_lshlrev_b32_e32 v66, 1, v66
	s_mov_b64 s[6:7], 0x1cc00000
	v_cndmask_b32_e32 v117, v117, v118, vcc
	v_rsq_f32_e32 v117, v117
	s_nop 0
	v_mul_f32_e32 v118, 0x45800000, v117
	v_cndmask_b32_e32 v118, v117, v118, vcc
	v_pk_mul_f32 v[110:111], v[110:111], v[118:119] op_sel_hi:[1,0]
	v_pk_mul_f32 v[106:107], v[106:107], v[118:119] op_sel_hi:[1,0]
	v_pk_fma_f32 v[62:63], v[2:3], v[110:111], v[62:63]
	v_pk_fma_f32 v[58:59], v[6:7], v[106:107], v[58:59]
	v_pk_mul_f32 v[102:103], v[102:103], v[118:119] op_sel_hi:[1,0]
	v_pk_mul_f32 v[112:113], v[112:113], v[118:119] op_sel_hi:[1,0]
	v_pk_mul_f32 v[108:109], v[108:109], v[118:119] op_sel_hi:[1,0]
	v_mul_f32_e32 v106, v63, v63
	v_pk_fma_f32 v[54:55], v[10:11], v[102:103], v[54:55]
	v_mul_f32_e32 v102, v59, v59
	v_pk_mul_f32 v[98:99], v[98:99], v[118:119] op_sel_hi:[1,0]
	v_pk_mul_f32 v[92:93], v[92:93], v[118:119] op_sel_hi:[1,0]
	v_pk_mul_f32 v[84:85], v[84:85], v[118:119] op_sel_hi:[1,0]
	v_pk_fma_f32 v[64:65], v[4:5], v[112:113], v[64:65]
	v_pk_fma_f32 v[60:61], v[8:9], v[108:109], v[60:61]
	v_fmac_f32_e32 v106, v62, v62
	v_pk_mul_f32 v[104:105], v[104:105], v[118:119] op_sel_hi:[1,0]
	v_fmac_f32_e32 v102, v58, v58
	v_pk_fma_f32 v[50:51], v[14:15], v[98:99], v[50:51]
	v_mul_f32_e32 v98, v55, v55
	v_pk_fma_f32 v[46:47], v[18:19], v[92:93], v[46:47]
	v_pk_mul_f32 v[86:87], v[86:87], v[118:119] op_sel_hi:[1,0]
	v_pk_fma_f32 v[42:43], v[22:23], v[84:85], v[42:43]
	v_fmac_f32_e32 v106, v64, v64
	v_pk_fma_f32 v[56:57], v[12:13], v[104:105], v[56:57]
	v_fmac_f32_e32 v102, v60, v60
	v_pk_mul_f32 v[100:101], v[100:101], v[118:119] op_sel_hi:[1,0]
	v_fmac_f32_e32 v98, v54, v54
	v_pk_mul_f32 v[94:95], v[94:95], v[118:119] op_sel_hi:[1,0]
	v_mul_f32_e32 v92, v51, v51
	v_pk_fma_f32 v[44:45], v[24:25], v[86:87], v[44:45]
	v_mov_b32_e32 v86, v43
	v_mov_b32_e32 v87, v47
	v_fmac_f32_e32 v106, v65, v65
	v_fmac_f32_e32 v102, v61, v61
	v_pk_fma_f32 v[52:53], v[16:17], v[100:101], v[52:53]
	v_fmac_f32_e32 v98, v56, v56
	v_pk_fma_f32 v[48:49], v[20:21], v[94:95], v[48:49]
	v_fmac_f32_e32 v92, v50, v50
	v_pk_mul_f32 v[82:83], v[82:83], v[118:119] op_sel_hi:[1,0]
	v_mov_b32_e32 v84, v42
	v_mov_b32_e32 v85, v46
	v_pk_mul_f32 v[86:87], v[86:87], v[86:87]
	v_add_f32_e32 v102, v106, v102
	v_fmac_f32_e32 v98, v57, v57
	v_fmac_f32_e32 v92, v52, v52
	v_pk_mul_f32 v[80:81], v[80:81], v[118:119] op_sel_hi:[1,0]
	v_pk_fma_f32 v[40:41], v[28:29], v[82:83], v[40:41]
	v_mov_b32_e32 v82, v44
	v_mov_b32_e32 v83, v48
	v_pk_fma_f32 v[84:85], v[84:85], v[84:85], v[86:87]
	v_add_f32_e32 v98, v98, v102
	v_fmac_f32_e32 v92, v53, v53
	v_pk_fma_f32 v[38:39], v[26:27], v[80:81], v[38:39]
	v_mov_b32_e32 v80, v45
	v_mov_b32_e32 v81, v49
	v_pk_fma_f32 v[82:83], v[82:83], v[82:83], v[84:85]
	v_add_f32_e32 v92, v92, v98
	v_pk_fma_f32 v[80:81], v[80:81], v[80:81], v[82:83]
	v_pk_mul_f32 v[82:83], v[88:89], v[118:119] op_sel_hi:[1,0]
	v_add_f32_e32 v81, v81, v92
	v_pk_fma_f32 v[34:35], v[30:31], v[82:83], v[34:35]
	v_add_f32_e32 v92, v80, v81
	v_pk_mul_f32 v[80:81], v[90:91], v[118:119] op_sel_hi:[1,0]
	v_mov_b32_e32 v86, v35
	v_mov_b32_e32 v87, v39
	v_pk_fma_f32 v[36:37], v[32:33], v[80:81], v[36:37]
	v_mov_b32_e32 v84, v34
	v_mov_b32_e32 v85, v38
	v_pk_mul_f32 v[86:87], v[86:87], v[86:87]
	v_mov_b32_e32 v82, v36
	v_mov_b32_e32 v83, v40
	v_pk_fma_f32 v[84:85], v[84:85], v[84:85], v[86:87]
	v_mov_b32_e32 v80, v37
	v_mov_b32_e32 v81, v41
	v_pk_fma_f32 v[82:83], v[82:83], v[82:83], v[84:85]
	global_store_dwordx4 v[68:69], v[62:65], off
	v_pk_fma_f32 v[80:81], v[80:81], v[80:81], v[82:83]
	global_store_dwordx4 v[68:69], v[58:61], off offset:1024
	global_store_dwordx4 v[68:69], v[54:57], off offset:2048
	global_store_dwordx4 v[68:69], v[50:53], off offset:3072
	global_store_dwordx4 v[78:79], v[46:49], off
	v_add_f32_e32 v81, v81, v92
	v_add_f32_e32 v80, v80, v81
	ds_bpermute_b32 v67, v67, v80
	v_mov_b32_e32 v69, v1
	global_store_dwordx4 v[72:73], v[42:45], off
	global_store_dwordx4 v[74:75], v[38:41], off
	global_store_dwordx4 v[76:77], v[34:37], off
	s_waitcnt lgkmcnt(0)
	v_add_f32_e32 v67, v80, v67
	ds_bpermute_b32 v71, v71, v67
	s_waitcnt lgkmcnt(0)
	v_add_f32_e32 v67, v67, v71
	ds_bpermute_b32 v71, v96, v67
	s_waitcnt lgkmcnt(0)
	v_add_f32_e32 v67, v67, v71
	ds_bpermute_b32 v71, v97, v67
	s_waitcnt lgkmcnt(0)
	v_add_f32_e32 v67, v67, v71
	ds_bpermute_b32 v71, v114, v67
	s_waitcnt lgkmcnt(0)
	v_add_f32_e32 v67, v67, v71
	ds_bpermute_b32 v71, v115, v67
	s_waitcnt lgkmcnt(0)
	v_add_f32_e32 v67, v67, v71
	v_fmamk_f32 v67, v67, 0x3a000000, v212
	v_mul_f32_e32 v68, 0x4b800000, v67
	v_cmp_gt_f32_e32 vcc, s3, v67
	s_mov_b32 s3, 0x1cc00000
	s_nop 0
	v_cndmask_b32_e32 v67, v67, v68, vcc
	v_rsq_f32_e32 v67, v67
	s_nop 0
	v_mul_f32_e32 v68, 0x45800000, v67
	v_cndmask_b32_e32 v71, v67, v68, vcc
	v_mov_b32_e32 v67, v1
	v_lshl_add_u64 v[66:67], s[34:35], 0, v[66:67]
	v_lshlrev_b32_e32 v68, 1, v116
	v_mul_f32_e32 v62, v62, v71
	v_mul_f32_e32 v63, v63, v71
	v_lshl_add_u64 v[66:67], v[66:67], 0, v[68:69]
	v_cvt_pk_bf16_f32 v62, v62, v63
	v_mul_f32_e32 v63, v64, v71
	v_mul_f32_e32 v64, v65, v71
	v_cvt_pk_bf16_f32 v63, v63, v64
	v_add_co_u32_e32 v64, vcc, s3, v66
	v_mul_f32_e32 v58, v58, v71
	s_nop 0
	v_addc_co_u32_e32 v65, vcc, 0, v67, vcc
	v_mul_f32_e32 v59, v59, v71
	v_lshl_add_u64 v[68:69], v[66:67], 0, s[6:7]
	global_store_dwordx2 v[64:65], v[62:63], off
	v_cvt_pk_bf16_f32 v58, v58, v59
	v_mul_f32_e32 v59, v60, v71
	v_mul_f32_e32 v54, v54, v71
	v_mul_f32_e32 v55, v55, v71
	v_mul_f32_e32 v60, v61, v71
	v_cvt_pk_bf16_f32 v59, v59, v60
	global_store_dwordx2 v[68:69], v[58:59], off offset:512
	v_cvt_pk_bf16_f32 v54, v54, v55
	v_mul_f32_e32 v55, v56, v71
	v_mul_f32_e32 v50, v50, v71
	v_mul_f32_e32 v51, v51, v71
	v_mul_f32_e32 v56, v57, v71
	v_cvt_pk_bf16_f32 v55, v55, v56
	global_store_dwordx2 v[68:69], v[54:55], off offset:1024
	v_cvt_pk_bf16_f32 v50, v50, v51
	v_mul_f32_e32 v51, v52, v71
	v_mul_f32_e32 v46, v46, v71
	v_mul_f32_e32 v47, v47, v71
	v_mul_f32_e32 v52, v53, v71
	v_cvt_pk_bf16_f32 v51, v51, v52
	global_store_dwordx2 v[68:69], v[50:51], off offset:1536
	v_cvt_pk_bf16_f32 v46, v46, v47
	v_mul_f32_e32 v47, v48, v71
	v_mul_f32_e32 v42, v42, v71
	v_mul_f32_e32 v43, v43, v71
	v_mul_f32_e32 v48, v49, v71
	v_cvt_pk_bf16_f32 v47, v47, v48
	global_store_dwordx2 v[68:69], v[46:47], off offset:2048
	v_cvt_pk_bf16_f32 v42, v42, v43
	v_mul_f32_e32 v43, v44, v71
	v_mul_f32_e32 v38, v38, v71
	v_mul_f32_e32 v39, v39, v71
	v_mul_f32_e32 v44, v45, v71
	v_cvt_pk_bf16_f32 v43, v43, v44
	global_store_dwordx2 v[68:69], v[42:43], off offset:2560
	v_cvt_pk_bf16_f32 v38, v38, v39
	v_mul_f32_e32 v39, v40, v71
	v_mul_f32_e32 v34, v34, v71
	v_mul_f32_e32 v35, v35, v71
	v_mul_f32_e32 v40, v41, v71
	v_cvt_pk_bf16_f32 v39, v39, v40
	global_store_dwordx2 v[68:69], v[38:39], off offset:3072
	v_cvt_pk_bf16_f32 v34, v34, v35
	v_mul_f32_e32 v35, v36, v71
	v_mul_f32_e32 v36, v37, v71
	v_cvt_pk_bf16_f32 v35, v35, v36
	global_store_dwordx2 v[68:69], v[34:35], off offset:3584

; __device__ __forceinline__ int opaque_tid() { int t = threadIdx.x; asm volatile("" : "+v"(t)); return t; }
; __device__ __forceinline__ void phase_resid(const Params& p, const float* g, bool first, bool last, int nsplit) {
;     const int tid = opaque_tid(), lane = tid & 63, gw = (blockIdx.x * NTHREADS + tid) >> 6, nw = (gridDim.x * NTHREADS) >> 6;
;     float* h = (float*)(p.ws + WS_H); bf16_t* abf = (bf16_t*)(p.ws + WS_ABF);
;     const bf16_t* mix = (const bf16_t*)(p.ws + WS_MIX);
;     const float* part = (const float*)(p.ws + WS_PART);
;     f32x4 gv[8];
; #pragma unroll
;     for (int i = 0; i < 8; ++i) gv[i] = *(const f32x4*)(g + lane * 4 + 256 * i);
;     ...
;     if (gw < 16) {
;         const int row = PADR + gw;
;         f32x4 mv[8], hv[8];
; #pragma unroll
;         for (int i = 0; i < 8; ++i) { mv[i] = (f32x4){0.f, 0.f, 0.f, 0.f}; hv[i] = *(const f32x4*)(HROW(row) + lane * 4 + 256 * i); }
;         for (int sp = 0; sp < nsplit; ++sp) {
; #pragma unroll
;             for (int i = 0; i < 8; ++i) mv[i] += *(const f32x4*)(part + (size_t)(sp * 16 + gw) * DM + lane * 4 + 256 * i);
;         }
.LBB0_763:
	s_andn2_b64 vcc, exec, s[4:5]
	s_cbranch_vccnz .LBB0_1567
	v_readlane_b32 s0, v254, 56
	s_cmp_lt_i32 s0, 3
	s_mov_b64 s[0:1], -1
	s_cbranch_scc1 .LBB0_806
	v_readlane_b32 s0, v254, 56
	s_cmp_gt_i32 s0, 3
	s_mov_b64 s[0:1], -1
	s_cbranch_scc0 .LBB0_778
	s_cmp_lt_u32 s80, 2
	s_cbranch_scc1 .Lrd_p4
	s_sleep 127
.Lrd_p4:
	s_lshl_b32 s0, s90, 11
	s_ashr_i32 s1, s0, 31
	v_mov_b32_e32 v0, v210
	s_lshl_b64 s[0:1], s[0:1], 2
	s_add_u32 s0, s46, s0
	s_waitcnt vmcnt(0)
	v_lshlrev_b32_e32 v2, 2, v0
	v_and_b32_e32 v110, 0xfc, v2
	s_addc_u32 s1, s13, s1
	v_lshlrev_b32_e32 v98, 2, v110
	v_mov_b32_e32 v99, v1
	v_lshl_add_u64 v[18:19], s[0:1], 0, v[98:99]
	v_add_co_u32_e32 v30, vcc, 0x1000, v18
	global_load_dwordx4 v[2:5], v98, s[0:1]
	global_load_dwordx4 v[6:9], v98, s[0:1] offset:1024
	global_load_dwordx4 v[10:13], v98, s[0:1] offset:2048
	global_load_dwordx4 v[14:17], v98, s[0:1] offset:3072
	v_addc_co_u32_e32 v31, vcc, 0, v19, vcc
	global_load_dwordx4 v[18:21], v[30:31], off
	global_load_dwordx4 v[22:25], v[30:31], off offset:1024
	global_load_dwordx4 v[26:29], v[30:31], off offset:2048
	s_nop 0
	global_load_dwordx4 v[30:33], v[30:31], off offset:3072
	s_add_i32 s0, s31, 7
	s_cmp_lt_u32 s0, 17
	v_readlane_b32 s2, v252, 5
	s_cselect_b64 s[0:1], -1, 0
	s_add_u32 s8, s34, 0x18a00000
	v_add_u32_e32 v34, s2, v0
	s_movk_i32 s2, 0x400
	s_addc_u32 s9, s35, 0
	v_lshrrev_b32_e32 v66, 6, v34
	v_cmp_gt_u32_e32 vcc, s2, v34
	v_and_b32_e32 v140, 63, v0
	s_and_saveexec_b64 s[4:5], vcc
	s_cbranch_execz .LBB0_770
	v_lshlrev_b32_e32 v34, 11, v66
	v_or_b32_e32 v0, 0x78000, v34
	v_mov_b32_e32 v35, v1
	v_lshl_add_u64 v[68:69], v[0:1], 2, s[8:9]
	v_lshl_add_u64 v[34:35], v[34:35], 2, s[40:41]
	v_cndmask_b32_e64 v35, v69, v35, s[0:1]
	v_cndmask_b32_e64 v34, v68, v34, s[0:1]
	v_lshl_add_u64 v[34:35], v[34:35], 0, v[98:99]
	s_movk_i32 s2, 0x1000
	global_load_dwordx4 v[62:65], v[34:35], off
	global_load_dwordx4 v[58:61], v[34:35], off offset:1024
	global_load_dwordx4 v[54:57], v[34:35], off offset:2048
	global_load_dwordx4 v[50:53], v[34:35], off offset:3072
	v_add_co_u32_e32 v34, vcc, s2, v34
	v_mov_b32_e32 v67, v1
	s_nop 0
	v_addc_co_u32_e32 v35, vcc, 0, v35, vcc
	global_load_dwordx4 v[46:49], v[34:35], off
	global_load_dwordx4 v[42:45], v[34:35], off offset:1024
	global_load_dwordx4 v[38:41], v[34:35], off offset:2048
	s_nop 0
	global_load_dwordx4 v[34:37], v[34:35], off offset:3072
	v_lshlrev_b64 v[70:71], 13, v[66:67]
	v_lshl_or_b32 v70, v140, 4, v70
	v_mov_b32_e32 v102, 0
	v_lshl_add_u64 v[70:71], s[34:35], 0, v[70:71]
	s_mov_b64 s[10:11], 0
	v_mov_b32_e32 v103, v102
	v_mov_b32_e32 v104, v102
	v_mov_b32_e32 v105, v102
	v_mov_b32_e32 v72, v102
	v_mov_b32_e32 v73, v102
	v_mov_b32_e32 v74, v102
	v_mov_b32_e32 v75, v102
	v_mov_b32_e32 v76, v102
	v_mov_b32_e32 v77, v102
	v_mov_b32_e32 v78, v102
	v_mov_b32_e32 v79, v102
	v_mov_b32_e32 v80, v102
	v_mov_b32_e32 v81, v102
	v_mov_b32_e32 v82, v102
	v_mov_b32_e32 v83, v102
	v_mov_b32_e32 v88, v102
	v_mov_b32_e32 v89, v102
	v_mov_b32_e32 v84, v102
	v_mov_b32_e32 v85, v102
	v_mov_b32_e32 v90, v102
	v_mov_b32_e32 v91, v102
	v_mov_b32_e32 v86, v102
	v_mov_b32_e32 v87, v102
	v_mov_b32_e32 v94, v102
	v_mov_b32_e32 v95, v102
	v_mov_b32_e32 v92, v102
	v_mov_b32_e32 v93, v102
	v_mov_b32_e32 v100, v102
	v_mov_b32_e32 v101, v102
	v_mov_b32_e32 v96, v102
	v_mov_b32_e32 v97, v102
	s_mov_b32 s3, 0x415c8000
	s_mov_b32 s6, 0x415c9000
	s_mov_b32 s7, 0x415ca000
	s_mov_b32 s12, 0x415e8000
	s_mov_b32 s13, 0x415e9000
	s_mov_b32 s14, 0x415ea000
	v_subrev_u32_e32 v141, s34, v70
	v_add_u32_e32 v142, 0x1000, v141
	v_add_u32_e32 v143, 0x2000, v141
	s_add_u32 s100, s34, 0x415c8000
	s_addc_u32 s101, s35, 0
	global_load_dwordx4 v[112:115], v141, s[100:101] offset:1280
	global_load_dwordx4 v[116:119], v141, s[100:101] offset:2304
	global_load_dwordx4 v[120:123], v141, s[100:101] offset:3328
	global_load_dwordx4 v[124:127], v142, s[100:101] offset:256
	global_load_dwordx4 v[128:131], v142, s[100:101] offset:1280
	global_load_dwordx4 v[132:135], v142, s[100:101] offset:2304
	global_load_dwordx4 v[136:139], v142, s[100:101] offset:3328
	global_load_dwordx4 v[144:147], v143, s[100:101] offset:256
	s_add_u32 s100, s100, 0x20000
	s_addc_u32 s101, s101, 0
	global_load_dwordx4 v[148:151], v141, s[100:101] offset:1280
	global_load_dwordx4 v[152:155], v141, s[100:101] offset:2304
	global_load_dwordx4 v[156:159], v141, s[100:101] offset:3328
	global_load_dwordx4 v[160:163], v142, s[100:101] offset:256
	global_load_dwordx4 v[164:167], v142, s[100:101] offset:1280
	global_load_dwordx4 v[168:171], v142, s[100:101] offset:2304
	global_load_dwordx4 v[172:175], v142, s[100:101] offset:3328
	global_load_dwordx4 v[176:179], v143, s[100:101] offset:256
	s_add_u32 s100, s100, 0x20000
	s_addc_u32 s101, s101, 0
	global_load_dwordx4 v[180:183], v141, s[100:101] offset:1280
	global_load_dwordx4 v[184:187], v141, s[100:101] offset:2304
	global_load_dwordx4 v[188:191], v141, s[100:101] offset:3328
	global_load_dwordx4 v[192:195], v142, s[100:101] offset:256
	global_load_dwordx4 v[196:199], v142, s[100:101] offset:1280
	global_load_dwordx4 v[200:203], v142, s[100:101] offset:2304
	global_load_dwordx4 v[204:207], v142, s[100:101] offset:3328
	global_load_dwordx4 v[224:227], v143, s[100:101] offset:256
	s_add_u32 s100, s100, 0x20000
	s_addc_u32 s101, s101, 0
	s_waitcnt vmcnt(23)
	v_pk_add_f32 v[100:101], v[100:101], v[112:113]
	v_pk_add_f32 v[96:97], v[96:97], v[114:115]
	global_load_dwordx4 v[112:115], v141, s[100:101] offset:1280
	s_waitcnt vmcnt(23)
	v_pk_add_f32 v[94:95], v[94:95], v[116:117]
	v_pk_add_f32 v[92:93], v[92:93], v[118:119]
	global_load_dwordx4 v[116:119], v141, s[100:101] offset:2304
	s_waitcnt vmcnt(23)
; __device__ __forceinline__ void phase_resid(const Params& p, const float* g, bool first, bool last, int nsplit) {
;     ...
;         for (int sp = 0; sp < nsplit; ++sp) {
; #pragma unroll
;             for (int i = 0; i < 8; ++i) mv[i] += *(const f32x4*)(part + (size_t)(sp * 16 + gw) * DM + lane * 4 + 256 * i);
;         }
	v_pk_add_f32 v[90:91], v[90:91], v[120:121]
	v_pk_add_f32 v[86:87], v[86:87], v[122:123]
	global_load_dwordx4 v[120:123], v141, s[100:101] offset:3328
	s_waitcnt vmcnt(23)
	v_pk_add_f32 v[88:89], v[88:89], v[124:125]
	v_pk_add_f32 v[84:85], v[84:85], v[126:127]
	global_load_dwordx4 v[124:127], v142, s[100:101] offset:256
	s_waitcnt vmcnt(23)
	v_pk_add_f32 v[80:81], v[80:81], v[128:129]
	v_pk_add_f32 v[82:83], v[82:83], v[130:131]
	global_load_dwordx4 v[128:131], v142, s[100:101] offset:1280
	s_waitcnt vmcnt(23)
	v_pk_add_f32 v[76:77], v[76:77], v[132:133]
	v_pk_add_f32 v[78:79], v[78:79], v[134:135]
	global_load_dwordx4 v[132:135], v142, s[100:101] offset:2304
	s_waitcnt vmcnt(23)
	v_pk_add_f32 v[72:73], v[72:73], v[136:137]
	v_pk_add_f32 v[74:75], v[74:75], v[138:139]
	global_load_dwordx4 v[136:139], v142, s[100:101] offset:3328
	s_waitcnt vmcnt(23)
	v_pk_add_f32 v[102:103], v[102:103], v[144:145]
	v_pk_add_f32 v[104:105], v[104:105], v[146:147]
	global_load_dwordx4 v[144:147], v143, s[100:101] offset:256
	s_add_u32 s100, s100, 0x20000
	s_addc_u32 s101, s101, 0
	s_waitcnt vmcnt(23)
	v_pk_add_f32 v[100:101], v[100:101], v[148:149]
	v_pk_add_f32 v[96:97], v[96:97], v[150:151]
	global_load_dwordx4 v[148:151], v141, s[100:101] offset:1280
	s_waitcnt vmcnt(23)
	v_pk_add_f32 v[94:95], v[94:95], v[152:153]
	v_pk_add_f32 v[92:93], v[92:93], v[154:155]
	global_load_dwordx4 v[152:155], v141, s[100:101] offset:2304
	s_waitcnt vmcnt(23)
	v_pk_add_f32 v[90:91], v[90:91], v[156:157]
	v_pk_add_f32 v[86:87], v[86:87], v[158:159]
	global_load_dwordx4 v[156:159], v141, s[100:101] offset:3328
	s_waitcnt vmcnt(23)
	v_pk_add_f32 v[88:89], v[88:89], v[160:161]
	v_pk_add_f32 v[84:85], v[84:85], v[162:163]
	global_load_dwordx4 v[160:163], v142, s[100:101] offset:256
	s_waitcnt vmcnt(23)
	v_pk_add_f32 v[80:81], v[80:81], v[164:165]
	v_pk_add_f32 v[82:83], v[82:83], v[166:167]
	global_load_dwordx4 v[164:167], v142, s[100:101] offset:1280
	s_waitcnt vmcnt(23)
	v_pk_add_f32 v[76:77], v[76:77], v[168:169]
	v_pk_add_f32 v[78:79], v[78:79], v[170:171]
	global_load_dwordx4 v[168:171], v142, s[100:101] offset:2304
	s_waitcnt vmcnt(23)
	v_pk_add_f32 v[72:73], v[72:73], v[172:173]
	v_pk_add_f32 v[74:75], v[74:75], v[174:175]
	global_load_dwordx4 v[172:175], v142, s[100:101] offset:3328
	s_waitcnt vmcnt(23)
	v_pk_add_f32 v[102:103], v[102:103], v[176:177]
	v_pk_add_f32 v[104:105], v[104:105], v[178:179]
	global_load_dwordx4 v[176:179], v143, s[100:101] offset:256
	s_add_u32 s100, s100, 0x20000
	s_addc_u32 s101, s101, 0
	s_waitcnt vmcnt(23)
	v_pk_add_f32 v[100:101], v[100:101], v[180:181]
	v_pk_add_f32 v[96:97], v[96:97], v[182:183]
	global_load_dwordx4 v[180:183], v141, s[100:101] offset:1280
	s_waitcnt vmcnt(23)
	v_pk_add_f32 v[94:95], v[94:95], v[184:185]
	v_pk_add_f32 v[92:93], v[92:93], v[186:187]
	global_load_dwordx4 v[184:187], v141, s[100:101] offset:2304
	s_waitcnt vmcnt(23)
	v_pk_add_f32 v[90:91], v[90:91], v[188:189]
	v_pk_add_f32 v[86:87], v[86:87], v[190:191]
	global_load_dwordx4 v[188:191], v141, s[100:101] offset:3328
	s_waitcnt vmcnt(23)
	v_pk_add_f32 v[88:89], v[88:89], v[192:193]
	v_pk_add_f32 v[84:85], v[84:85], v[194:195]
	global_load_dwordx4 v[192:195], v142, s[100:101] offset:256
	s_waitcnt vmcnt(23)
	v_pk_add_f32 v[80:81], v[80:81], v[196:197]
	v_pk_add_f32 v[82:83], v[82:83], v[198:199]
	global_load_dwordx4 v[196:199], v142, s[100:101] offset:1280
	s_waitcnt vmcnt(23)
	v_pk_add_f32 v[76:77], v[76:77], v[200:201]
	v_pk_add_f32 v[78:79], v[78:79], v[202:203]
	global_load_dwordx4 v[200:203], v142, s[100:101] offset:2304
	s_waitcnt vmcnt(23)
	v_pk_add_f32 v[72:73], v[72:73], v[204:205]
	v_pk_add_f32 v[74:75], v[74:75], v[206:207]
	global_load_dwordx4 v[204:207], v142, s[100:101] offset:3328
	s_waitcnt vmcnt(23)
	v_pk_add_f32 v[102:103], v[102:103], v[224:225]
	v_pk_add_f32 v[104:105], v[104:105], v[226:227]
	global_load_dwordx4 v[224:227], v143, s[100:101] offset:256
	s_add_u32 s100, s100, 0x20000
	s_addc_u32 s101, s101, 0
	s_waitcnt vmcnt(23)
	v_pk_add_f32 v[100:101], v[100:101], v[112:113]
	v_pk_add_f32 v[96:97], v[96:97], v[114:115]
	global_load_dwordx4 v[112:115], v141, s[100:101] offset:1280
	s_waitcnt vmcnt(23)
	v_pk_add_f32 v[94:95], v[94:95], v[116:117]
	v_pk_add_f32 v[92:93], v[92:93], v[118:119]
	global_load_dwordx4 v[116:119], v141, s[100:101] offset:2304
	s_waitcnt vmcnt(23)
	v_pk_add_f32 v[90:91], v[90:91], v[120:121]
	v_pk_add_f32 v[86:87], v[86:87], v[122:123]
	global_load_dwordx4 v[120:123], v141, s[100:101] offset:3328
	s_waitcnt vmcnt(23)
	v_pk_add_f32 v[88:89], v[88:89], v[124:125]
	v_pk_add_f32 v[84:85], v[84:85], v[126:127]
	global_load_dwordx4 v[124:127], v142, s[100:101] offset:256
	s_waitcnt vmcnt(23)
	v_pk_add_f32 v[80:81], v[80:81], v[128:129]
	v_pk_add_f32 v[82:83], v[82:83], v[130:131]
	global_load_dwordx4 v[128:131], v142, s[100:101] offset:1280
	s_waitcnt vmcnt(23)
	v_pk_add_f32 v[76:77], v[76:77], v[132:133]
	v_pk_add_f32 v[78:79], v[78:79], v[134:135]
	global_load_dwordx4 v[132:135], v142, s[100:101] offset:2304
	s_waitcnt vmcnt(23)
	v_pk_add_f32 v[72:73], v[72:73], v[136:137]
	v_pk_add_f32 v[74:75], v[74:75], v[138:139]
	global_load_dwordx4 v[136:139], v142, s[100:101] offset:3328
	s_waitcnt vmcnt(23)
	v_pk_add_f32 v[102:103], v[102:103], v[144:145]
	v_pk_add_f32 v[104:105], v[104:105], v[146:147]
	global_load_dwordx4 v[144:147], v143, s[100:101] offset:256
	s_add_u32 s100, s100, 0x20000
	s_addc_u32 s101, s101, 0
	s_waitcnt vmcnt(23)
	v_pk_add_f32 v[100:101], v[100:101], v[148:149]
	v_pk_add_f32 v[96:97], v[96:97], v[150:151]
	global_load_dwordx4 v[148:151], v141, s[100:101] offset:1280
	s_waitcnt vmcnt(23)
; __device__ __forceinline__ void phase_resid(const Params& p, const float* g, bool first, bool last, int nsplit) {
;     ...
;         for (int sp = 0; sp < nsplit; ++sp) {
; #pragma unroll
;             for (int i = 0; i < 8; ++i) mv[i] += *(const f32x4*)(part + (size_t)(sp * 16 + gw) * DM + lane * 4 + 256 * i);
;         }
	v_pk_add_f32 v[94:95], v[94:95], v[152:153]
	v_pk_add_f32 v[92:93], v[92:93], v[154:155]
	global_load_dwordx4 v[152:155], v141, s[100:101] offset:2304
	s_waitcnt vmcnt(23)
	v_pk_add_f32 v[90:91], v[90:91], v[156:157]
	v_pk_add_f32 v[86:87], v[86:87], v[158:159]
	global_load_dwordx4 v[156:159], v141, s[100:101] offset:3328
	s_waitcnt vmcnt(23)
	v_pk_add_f32 v[88:89], v[88:89], v[160:161]
	v_pk_add_f32 v[84:85], v[84:85], v[162:163]
	global_load_dwordx4 v[160:163], v142, s[100:101] offset:256
	s_waitcnt vmcnt(23)
	v_pk_add_f32 v[80:81], v[80:81], v[164:165]
	v_pk_add_f32 v[82:83], v[82:83], v[166:167]
	global_load_dwordx4 v[164:167], v142, s[100:101] offset:1280
	s_waitcnt vmcnt(23)
	v_pk_add_f32 v[76:77], v[76:77], v[168:169]
	v_pk_add_f32 v[78:79], v[78:79], v[170:171]
	global_load_dwordx4 v[168:171], v142, s[100:101] offset:2304
	s_waitcnt vmcnt(23)
	v_pk_add_f32 v[72:73], v[72:73], v[172:173]
	v_pk_add_f32 v[74:75], v[74:75], v[174:175]
	global_load_dwordx4 v[172:175], v142, s[100:101] offset:3328
	s_waitcnt vmcnt(23)
	v_pk_add_f32 v[102:103], v[102:103], v[176:177]
	v_pk_add_f32 v[104:105], v[104:105], v[178:179]
	global_load_dwordx4 v[176:179], v143, s[100:101] offset:256
	s_add_u32 s100, s100, 0x20000
	s_addc_u32 s101, s101, 0
	s_waitcnt vmcnt(23)
	v_pk_add_f32 v[100:101], v[100:101], v[180:181]
	v_pk_add_f32 v[96:97], v[96:97], v[182:183]
	global_load_dwordx4 v[180:183], v141, s[100:101] offset:1280
	s_waitcnt vmcnt(23)
	v_pk_add_f32 v[94:95], v[94:95], v[184:185]
	v_pk_add_f32 v[92:93], v[92:93], v[186:187]
	global_load_dwordx4 v[184:187], v141, s[100:101] offset:2304
	s_waitcnt vmcnt(23)
	v_pk_add_f32 v[90:91], v[90:91], v[188:189]
	v_pk_add_f32 v[86:87], v[86:87], v[190:191]
	global_load_dwordx4 v[188:191], v141, s[100:101] offset:3328
	s_waitcnt vmcnt(23)
	v_pk_add_f32 v[88:89], v[88:89], v[192:193]
	v_pk_add_f32 v[84:85], v[84:85], v[194:195]
	global_load_dwordx4 v[192:195], v142, s[100:101] offset:256
	s_waitcnt vmcnt(23)
	v_pk_add_f32 v[80:81], v[80:81], v[196:197]
	v_pk_add_f32 v[82:83], v[82:83], v[198:199]
	global_load_dwordx4 v[196:199], v142, s[100:101] offset:1280
	s_waitcnt vmcnt(23)
	v_pk_add_f32 v[76:77], v[76:77], v[200:201]
	v_pk_add_f32 v[78:79], v[78:79], v[202:203]
	global_load_dwordx4 v[200:203], v142, s[100:101] offset:2304
	s_waitcnt vmcnt(23)
	v_pk_add_f32 v[72:73], v[72:73], v[204:205]
	v_pk_add_f32 v[74:75], v[74:75], v[206:207]
	global_load_dwordx4 v[204:207], v142, s[100:101] offset:3328
	s_waitcnt vmcnt(23)
	v_pk_add_f32 v[102:103], v[102:103], v[224:225]
	v_pk_add_f32 v[104:105], v[104:105], v[226:227]
	global_load_dwordx4 v[224:227], v143, s[100:101] offset:256
	s_add_u32 s100, s100, 0x20000
	s_addc_u32 s101, s101, 0
	s_waitcnt vmcnt(23)
	v_pk_add_f32 v[100:101], v[100:101], v[112:113]
	v_pk_add_f32 v[96:97], v[96:97], v[114:115]
	global_load_dwordx4 v[112:115], v141, s[100:101] offset:1280
	s_waitcnt vmcnt(23)
	v_pk_add_f32 v[94:95], v[94:95], v[116:117]
	v_pk_add_f32 v[92:93], v[92:93], v[118:119]
	global_load_dwordx4 v[116:119], v141, s[100:101] offset:2304
	s_waitcnt vmcnt(23)
	v_pk_add_f32 v[90:91], v[90:91], v[120:121]
	v_pk_add_f32 v[86:87], v[86:87], v[122:123]
	global_load_dwordx4 v[120:123], v141, s[100:101] offset:3328
	s_waitcnt vmcnt(23)
	v_pk_add_f32 v[88:89], v[88:89], v[124:125]
	v_pk_add_f32 v[84:85], v[84:85], v[126:127]
	global_load_dwordx4 v[124:127], v142, s[100:101] offset:256
	s_waitcnt vmcnt(23)
	v_pk_add_f32 v[80:81], v[80:81], v[128:129]
	v_pk_add_f32 v[82:83], v[82:83], v[130:131]
	global_load_dwordx4 v[128:131], v142, s[100:101] offset:1280
	s_waitcnt vmcnt(23)
	v_pk_add_f32 v[76:77], v[76:77], v[132:133]
	v_pk_add_f32 v[78:79], v[78:79], v[134:135]
	global_load_dwordx4 v[132:135], v142, s[100:101] offset:2304
	s_waitcnt vmcnt(23)
	v_pk_add_f32 v[72:73], v[72:73], v[136:137]
	v_pk_add_f32 v[74:75], v[74:75], v[138:139]
	global_load_dwordx4 v[136:139], v142, s[100:101] offset:3328
	s_waitcnt vmcnt(23)
	v_pk_add_f32 v[102:103], v[102:103], v[144:145]
	v_pk_add_f32 v[104:105], v[104:105], v[146:147]
	global_load_dwordx4 v[144:147], v143, s[100:101] offset:256
	s_add_u32 s100, s100, 0x20000
	s_addc_u32 s101, s101, 0
	s_waitcnt vmcnt(23)
	v_pk_add_f32 v[100:101], v[100:101], v[148:149]
	v_pk_add_f32 v[96:97], v[96:97], v[150:151]
	global_load_dwordx4 v[148:151], v141, s[100:101] offset:1280
	s_waitcnt vmcnt(23)
	v_pk_add_f32 v[94:95], v[94:95], v[152:153]
	v_pk_add_f32 v[92:93], v[92:93], v[154:155]
	global_load_dwordx4 v[152:155], v141, s[100:101] offset:2304
	s_waitcnt vmcnt(23)
	v_pk_add_f32 v[90:91], v[90:91], v[156:157]
	v_pk_add_f32 v[86:87], v[86:87], v[158:159]
	global_load_dwordx4 v[156:159], v141, s[100:101] offset:3328
	s_waitcnt vmcnt(23)
	v_pk_add_f32 v[88:89], v[88:89], v[160:161]
	v_pk_add_f32 v[84:85], v[84:85], v[162:163]
	global_load_dwordx4 v[160:163], v142, s[100:101] offset:256
	s_waitcnt vmcnt(23)
	v_pk_add_f32 v[80:81], v[80:81], v[164:165]
	v_pk_add_f32 v[82:83], v[82:83], v[166:167]
	global_load_dwordx4 v[164:167], v142, s[100:101] offset:1280
	s_waitcnt vmcnt(23)
	v_pk_add_f32 v[76:77], v[76:77], v[168:169]
	v_pk_add_f32 v[78:79], v[78:79], v[170:171]
	global_load_dwordx4 v[168:171], v142, s[100:101] offset:2304
	s_waitcnt vmcnt(23)
	v_pk_add_f32 v[72:73], v[72:73], v[172:173]
	v_pk_add_f32 v[74:75], v[74:75], v[174:175]
	global_load_dwordx4 v[172:175], v142, s[100:101] offset:3328
	s_waitcnt vmcnt(23)
	v_pk_add_f32 v[102:103], v[102:103], v[176:177]
	v_pk_add_f32 v[104:105], v[104:105], v[178:179]
	global_load_dwordx4 v[176:179], v143, s[100:101] offset:256
	s_add_u32 s100, s100, 0x20000
	s_addc_u32 s101, s101, 0
	s_waitcnt vmcnt(23)
; __device__ __forceinline__ void phase_resid(const Params& p, const float* g, bool first, bool last, int nsplit) {
;     ...
;         for (int sp = 0; sp < nsplit; ++sp) {
; #pragma unroll
;             for (int i = 0; i < 8; ++i) mv[i] += *(const f32x4*)(part + (size_t)(sp * 16 + gw) * DM + lane * 4 + 256 * i);
;         }
	v_pk_add_f32 v[100:101], v[100:101], v[180:181]
	v_pk_add_f32 v[96:97], v[96:97], v[182:183]
	global_load_dwordx4 v[180:183], v141, s[100:101] offset:1280
	s_waitcnt vmcnt(23)
	v_pk_add_f32 v[94:95], v[94:95], v[184:185]
	v_pk_add_f32 v[92:93], v[92:93], v[186:187]
	global_load_dwordx4 v[184:187], v141, s[100:101] offset:2304
	s_waitcnt vmcnt(23)
	v_pk_add_f32 v[90:91], v[90:91], v[188:189]
	v_pk_add_f32 v[86:87], v[86:87], v[190:191]
	global_load_dwordx4 v[188:191], v141, s[100:101] offset:3328
	s_waitcnt vmcnt(23)
	v_pk_add_f32 v[88:89], v[88:89], v[192:193]
	v_pk_add_f32 v[84:85], v[84:85], v[194:195]
	global_load_dwordx4 v[192:195], v142, s[100:101] offset:256
	s_waitcnt vmcnt(23)
	v_pk_add_f32 v[80:81], v[80:81], v[196:197]
	v_pk_add_f32 v[82:83], v[82:83], v[198:199]
	global_load_dwordx4 v[196:199], v142, s[100:101] offset:1280
	s_waitcnt vmcnt(23)
	v_pk_add_f32 v[76:77], v[76:77], v[200:201]
	v_pk_add_f32 v[78:79], v[78:79], v[202:203]
	global_load_dwordx4 v[200:203], v142, s[100:101] offset:2304
	s_waitcnt vmcnt(23)
	v_pk_add_f32 v[72:73], v[72:73], v[204:205]
	v_pk_add_f32 v[74:75], v[74:75], v[206:207]
	global_load_dwordx4 v[204:207], v142, s[100:101] offset:3328
	s_waitcnt vmcnt(23)
	v_pk_add_f32 v[102:103], v[102:103], v[224:225]
	v_pk_add_f32 v[104:105], v[104:105], v[226:227]
	global_load_dwordx4 v[224:227], v143, s[100:101] offset:256
	s_add_u32 s100, s100, 0x20000
	s_addc_u32 s101, s101, 0
	s_waitcnt vmcnt(23)
	v_pk_add_f32 v[100:101], v[100:101], v[112:113]
	v_pk_add_f32 v[96:97], v[96:97], v[114:115]
	global_load_dwordx4 v[112:115], v141, s[100:101] offset:1280
	s_waitcnt vmcnt(23)
	v_pk_add_f32 v[94:95], v[94:95], v[116:117]
	v_pk_add_f32 v[92:93], v[92:93], v[118:119]
	global_load_dwordx4 v[116:119], v141, s[100:101] offset:2304
	s_waitcnt vmcnt(23)
	v_pk_add_f32 v[90:91], v[90:91], v[120:121]
	v_pk_add_f32 v[86:87], v[86:87], v[122:123]
	global_load_dwordx4 v[120:123], v141, s[100:101] offset:3328
	s_waitcnt vmcnt(23)
	v_pk_add_f32 v[88:89], v[88:89], v[124:125]
	v_pk_add_f32 v[84:85], v[84:85], v[126:127]
	global_load_dwordx4 v[124:127], v142, s[100:101] offset:256
	s_waitcnt vmcnt(23)
	v_pk_add_f32 v[80:81], v[80:81], v[128:129]
	v_pk_add_f32 v[82:83], v[82:83], v[130:131]
	global_load_dwordx4 v[128:131], v142, s[100:101] offset:1280
	s_waitcnt vmcnt(23)
	v_pk_add_f32 v[76:77], v[76:77], v[132:133]
	v_pk_add_f32 v[78:79], v[78:79], v[134:135]
	global_load_dwordx4 v[132:135], v142, s[100:101] offset:2304
	s_waitcnt vmcnt(23)
	v_pk_add_f32 v[72:73], v[72:73], v[136:137]
	v_pk_add_f32 v[74:75], v[74:75], v[138:139]
	global_load_dwordx4 v[136:139], v142, s[100:101] offset:3328
	s_waitcnt vmcnt(23)
	v_pk_add_f32 v[102:103], v[102:103], v[144:145]
	v_pk_add_f32 v[104:105], v[104:105], v[146:147]
	global_load_dwordx4 v[144:147], v143, s[100:101] offset:256
	s_add_u32 s100, s100, 0x20000
	s_addc_u32 s101, s101, 0
	s_waitcnt vmcnt(23)
	v_pk_add_f32 v[100:101], v[100:101], v[148:149]
	v_pk_add_f32 v[96:97], v[96:97], v[150:151]
	global_load_dwordx4 v[148:151], v141, s[100:101] offset:1280
	s_waitcnt vmcnt(23)
	v_pk_add_f32 v[94:95], v[94:95], v[152:153]
	v_pk_add_f32 v[92:93], v[92:93], v[154:155]
	global_load_dwordx4 v[152:155], v141, s[100:101] offset:2304
	s_waitcnt vmcnt(23)
	v_pk_add_f32 v[90:91], v[90:91], v[156:157]
	v_pk_add_f32 v[86:87], v[86:87], v[158:159]
	global_load_dwordx4 v[156:159], v141, s[100:101] offset:3328
	s_waitcnt vmcnt(23)
	v_pk_add_f32 v[88:89], v[88:89], v[160:161]
	v_pk_add_f32 v[84:85], v[84:85], v[162:163]
	global_load_dwordx4 v[160:163], v142, s[100:101] offset:256
	s_waitcnt vmcnt(23)
	v_pk_add_f32 v[80:81], v[80:81], v[164:165]
	v_pk_add_f32 v[82:83], v[82:83], v[166:167]
	global_load_dwordx4 v[164:167], v142, s[100:101] offset:1280
	s_waitcnt vmcnt(23)
	v_pk_add_f32 v[76:77], v[76:77], v[168:169]
	v_pk_add_f32 v[78:79], v[78:79], v[170:171]
	global_load_dwordx4 v[168:171], v142, s[100:101] offset:2304
	s_waitcnt vmcnt(23)
	v_pk_add_f32 v[72:73], v[72:73], v[172:173]
	v_pk_add_f32 v[74:75], v[74:75], v[174:175]
	global_load_dwordx4 v[172:175], v142, s[100:101] offset:3328
	s_waitcnt vmcnt(23)
	v_pk_add_f32 v[102:103], v[102:103], v[176:177]
	v_pk_add_f32 v[104:105], v[104:105], v[178:179]
	global_load_dwordx4 v[176:179], v143, s[100:101] offset:256
	s_add_u32 s100, s100, 0x20000
	s_addc_u32 s101, s101, 0
	s_waitcnt vmcnt(23)
	v_pk_add_f32 v[100:101], v[100:101], v[180:181]
	v_pk_add_f32 v[96:97], v[96:97], v[182:183]
	global_load_dwordx4 v[180:183], v141, s[100:101] offset:1280
	s_waitcnt vmcnt(23)
	v_pk_add_f32 v[94:95], v[94:95], v[184:185]
	v_pk_add_f32 v[92:93], v[92:93], v[186:187]
	global_load_dwordx4 v[184:187], v141, s[100:101] offset:2304
	s_waitcnt vmcnt(23)
	v_pk_add_f32 v[90:91], v[90:91], v[188:189]
	v_pk_add_f32 v[86:87], v[86:87], v[190:191]
	global_load_dwordx4 v[188:191], v141, s[100:101] offset:3328
	s_waitcnt vmcnt(23)
	v_pk_add_f32 v[88:89], v[88:89], v[192:193]
	v_pk_add_f32 v[84:85], v[84:85], v[194:195]
	global_load_dwordx4 v[192:195], v142, s[100:101] offset:256
	s_waitcnt vmcnt(23)
	v_pk_add_f32 v[80:81], v[80:81], v[196:197]
	v_pk_add_f32 v[82:83], v[82:83], v[198:199]
	global_load_dwordx4 v[196:199], v142, s[100:101] offset:1280
	s_waitcnt vmcnt(23)
	v_pk_add_f32 v[76:77], v[76:77], v[200:201]
	v_pk_add_f32 v[78:79], v[78:79], v[202:203]
	global_load_dwordx4 v[200:203], v142, s[100:101] offset:2304
	s_waitcnt vmcnt(23)
	v_pk_add_f32 v[72:73], v[72:73], v[204:205]
	v_pk_add_f32 v[74:75], v[74:75], v[206:207]
	global_load_dwordx4 v[204:207], v142, s[100:101] offset:3328
	s_waitcnt vmcnt(23)
; __device__ __forceinline__ void phase_resid(const Params& p, const float* g, bool first, bool last, int nsplit) {
;     ...
;         for (int sp = 0; sp < nsplit; ++sp) {
; #pragma unroll
;             for (int i = 0; i < 8; ++i) mv[i] += *(const f32x4*)(part + (size_t)(sp * 16 + gw) * DM + lane * 4 + 256 * i);
;         }
	v_pk_add_f32 v[102:103], v[102:103], v[224:225]
	v_pk_add_f32 v[104:105], v[104:105], v[226:227]
	global_load_dwordx4 v[224:227], v143, s[100:101] offset:256
	s_add_u32 s100, s100, 0x20000
	s_addc_u32 s101, s101, 0
	s_waitcnt vmcnt(23)
	v_pk_add_f32 v[100:101], v[100:101], v[112:113]
	v_pk_add_f32 v[96:97], v[96:97], v[114:115]
	global_load_dwordx4 v[112:115], v141, s[100:101] offset:1280
	s_waitcnt vmcnt(23)
	v_pk_add_f32 v[94:95], v[94:95], v[116:117]
	v_pk_add_f32 v[92:93], v[92:93], v[118:119]
	global_load_dwordx4 v[116:119], v141, s[100:101] offset:2304
	s_waitcnt vmcnt(23)
	v_pk_add_f32 v[90:91], v[90:91], v[120:121]
	v_pk_add_f32 v[86:87], v[86:87], v[122:123]
	global_load_dwordx4 v[120:123], v141, s[100:101] offset:3328
	s_waitcnt vmcnt(23)
	v_pk_add_f32 v[88:89], v[88:89], v[124:125]
	v_pk_add_f32 v[84:85], v[84:85], v[126:127]
	global_load_dwordx4 v[124:127], v142, s[100:101] offset:256
	s_waitcnt vmcnt(23)
	v_pk_add_f32 v[80:81], v[80:81], v[128:129]
	v_pk_add_f32 v[82:83], v[82:83], v[130:131]
	global_load_dwordx4 v[128:131], v142, s[100:101] offset:1280
	s_waitcnt vmcnt(23)
	v_pk_add_f32 v[76:77], v[76:77], v[132:133]
	v_pk_add_f32 v[78:79], v[78:79], v[134:135]
	global_load_dwordx4 v[132:135], v142, s[100:101] offset:2304
	s_waitcnt vmcnt(23)
	v_pk_add_f32 v[72:73], v[72:73], v[136:137]
	v_pk_add_f32 v[74:75], v[74:75], v[138:139]
	global_load_dwordx4 v[136:139], v142, s[100:101] offset:3328
	s_waitcnt vmcnt(23)
	v_pk_add_f32 v[102:103], v[102:103], v[144:145]
	v_pk_add_f32 v[104:105], v[104:105], v[146:147]
	global_load_dwordx4 v[144:147], v143, s[100:101] offset:256
	s_waitcnt vmcnt(23)
	v_pk_add_f32 v[100:101], v[100:101], v[148:149]
	v_pk_add_f32 v[96:97], v[96:97], v[150:151]
	s_waitcnt vmcnt(22)
	v_pk_add_f32 v[94:95], v[94:95], v[152:153]
	v_pk_add_f32 v[92:93], v[92:93], v[154:155]
	s_waitcnt vmcnt(21)
	v_pk_add_f32 v[90:91], v[90:91], v[156:157]
	v_pk_add_f32 v[86:87], v[86:87], v[158:159]
	s_waitcnt vmcnt(20)
	v_pk_add_f32 v[88:89], v[88:89], v[160:161]
	v_pk_add_f32 v[84:85], v[84:85], v[162:163]
	s_waitcnt vmcnt(19)
	v_pk_add_f32 v[80:81], v[80:81], v[164:165]
	v_pk_add_f32 v[82:83], v[82:83], v[166:167]
	s_waitcnt vmcnt(18)
	v_pk_add_f32 v[76:77], v[76:77], v[168:169]
	v_pk_add_f32 v[78:79], v[78:79], v[170:171]
	s_waitcnt vmcnt(17)
	v_pk_add_f32 v[72:73], v[72:73], v[172:173]
	v_pk_add_f32 v[74:75], v[74:75], v[174:175]
	s_waitcnt vmcnt(16)
	v_pk_add_f32 v[102:103], v[102:103], v[176:177]
	v_pk_add_f32 v[104:105], v[104:105], v[178:179]
	s_waitcnt vmcnt(15)
	v_pk_add_f32 v[100:101], v[100:101], v[180:181]
	v_pk_add_f32 v[96:97], v[96:97], v[182:183]
	s_waitcnt vmcnt(14)
	v_pk_add_f32 v[94:95], v[94:95], v[184:185]
	v_pk_add_f32 v[92:93], v[92:93], v[186:187]
	s_waitcnt vmcnt(13)
	v_pk_add_f32 v[90:91], v[90:91], v[188:189]
	v_pk_add_f32 v[86:87], v[86:87], v[190:191]
	s_waitcnt vmcnt(12)
	v_pk_add_f32 v[88:89], v[88:89], v[192:193]
	v_pk_add_f32 v[84:85], v[84:85], v[194:195]
	s_waitcnt vmcnt(11)
	v_pk_add_f32 v[80:81], v[80:81], v[196:197]
	v_pk_add_f32 v[82:83], v[82:83], v[198:199]
	s_waitcnt vmcnt(10)
	v_pk_add_f32 v[76:77], v[76:77], v[200:201]
	v_pk_add_f32 v[78:79], v[78:79], v[202:203]
	s_waitcnt vmcnt(9)
	v_pk_add_f32 v[72:73], v[72:73], v[204:205]
	v_pk_add_f32 v[74:75], v[74:75], v[206:207]
	s_waitcnt vmcnt(8)
	v_pk_add_f32 v[102:103], v[102:103], v[224:225]
	v_pk_add_f32 v[104:105], v[104:105], v[226:227]
	s_waitcnt vmcnt(7)
	v_pk_add_f32 v[100:101], v[100:101], v[112:113]
	v_pk_add_f32 v[96:97], v[96:97], v[114:115]
	s_waitcnt vmcnt(6)
	v_pk_add_f32 v[94:95], v[94:95], v[116:117]
	v_pk_add_f32 v[92:93], v[92:93], v[118:119]
	s_waitcnt vmcnt(5)
	v_pk_add_f32 v[90:91], v[90:91], v[120:121]
	v_pk_add_f32 v[86:87], v[86:87], v[122:123]
	s_waitcnt vmcnt(4)
	v_pk_add_f32 v[88:89], v[88:89], v[124:125]
	v_pk_add_f32 v[84:85], v[84:85], v[126:127]
	s_waitcnt vmcnt(3)
	v_pk_add_f32 v[80:81], v[80:81], v[128:129]
	v_pk_add_f32 v[82:83], v[82:83], v[130:131]
	s_waitcnt vmcnt(2)
	v_pk_add_f32 v[76:77], v[76:77], v[132:133]
	v_pk_add_f32 v[78:79], v[78:79], v[134:135]
	s_waitcnt vmcnt(1)
	v_pk_add_f32 v[72:73], v[72:73], v[136:137]
	v_pk_add_f32 v[74:75], v[74:75], v[138:139]
	s_waitcnt vmcnt(0) lgkmcnt(0)
	v_pk_add_f32 v[102:103], v[102:103], v[144:145]
	v_pk_add_f32 v[104:105], v[104:105], v[146:147]
	s_mov_b32 s10, 0x200000
	v_mul_f32_e32 v67, v101, v101
	v_mul_f32_e32 v70, v95, v95
	v_fmac_f32_e32 v67, v100, v100
	v_fmac_f32_e32 v70, v94, v94
	v_fmac_f32_e32 v67, v96, v96
	v_fmac_f32_e32 v70, v92, v92
	v_fmac_f32_e32 v67, v97, v97
	v_fmac_f32_e32 v70, v93, v93
	v_add_f32_e32 v67, v67, v70
	v_mul_f32_e32 v70, v91, v91
	v_fmac_f32_e32 v70, v90, v90
	v_fmac_f32_e32 v70, v86, v86
	v_fmac_f32_e32 v70, v87, v87
	v_add_f32_e32 v67, v67, v70
	v_mul_f32_e32 v70, v89, v89
	v_fmac_f32_e32 v70, v88, v88
	v_fmac_f32_e32 v70, v84, v84
	v_fmac_f32_e32 v70, v85, v85
	v_mov_b32_e32 v106, v81
	v_mov_b32_e32 v107, v77
	v_add_f32_e32 v67, v67, v70
	v_mov_b32_e32 v70, v80
	v_mov_b32_e32 v71, v76
	v_pk_mul_f32 v[106:107], v[106:107], v[106:107]
	s_mov_b32 s3, 0x800000
	v_pk_fma_f32 v[70:71], v[70:71], v[70:71], v[106:107]
	v_mov_b32_e32 v106, v82
	v_mov_b32_e32 v107, v78
	v_pk_fma_f32 v[70:71], v[106:107], v[106:107], v[70:71]
	v_mov_b32_e32 v106, v83
	v_mov_b32_e32 v107, v79
	v_pk_fma_f32 v[70:71], v[106:107], v[106:107], v[70:71]
	v_mov_b32_e32 v106, v73
	v_add_f32_e32 v67, v67, v70
	v_mov_b32_e32 v107, v103
	v_add_f32_e32 v67, v67, v71
	v_mov_b32_e32 v70, v72
	v_mov_b32_e32 v71, v102
	v_pk_mul_f32 v[106:107], v[106:107], v[106:107]
	s_movk_i32 s2, 0x1000
	v_pk_fma_f32 v[70:71], v[70:71], v[70:71], v[106:107]
	v_mov_b32_e32 v106, v74
	v_mov_b32_e32 v107, v104
	v_pk_fma_f32 v[70:71], v[106:107], v[106:107], v[70:71]
	v_mov_b32_e32 v106, v75
	v_mov_b32_e32 v107, v105
	v_pk_fma_f32 v[70:71], v[106:107], v[106:107], v[70:71]
	v_lshlrev_b32_e32 v0, 1, v0
	v_add_f32_e32 v67, v67, v70
	v_and_b32_e32 v70, 64, v215
	v_add_f32_e32 v67, v67, v71
	v_add_u32_e32 v70, 64, v70
	v_xor_b32_e32 v71, 32, v215
	v_cmp_lt_i32_e32 vcc, v71, v70
	s_nop 1
	v_cndmask_b32_e32 v71, v215, v71, vcc
	v_lshlrev_b32_e32 v99, 2, v71
	ds_bpermute_b32 v71, v99, v67
	s_waitcnt lgkmcnt(0)
	v_add_f32_e32 v67, v67, v71
	v_xor_b32_e32 v71, 16, v215
	v_cmp_lt_i32_e32 vcc, v71, v70
	s_nop 1
	v_cndmask_b32_e32 v71, v215, v71, vcc
	v_lshlrev_b32_e32 v106, 2, v71
	ds_bpermute_b32 v71, v106, v67
	s_waitcnt lgkmcnt(0)
	v_add_f32_e32 v67, v67, v71
	v_xor_b32_e32 v71, 8, v215
	v_cmp_lt_i32_e32 vcc, v71, v70
	s_nop 1
	v_cndmask_b32_e32 v71, v215, v71, vcc
	v_lshlrev_b32_e32 v107, 2, v71
	ds_bpermute_b32 v71, v107, v67
	s_waitcnt lgkmcnt(0)
	v_add_f32_e32 v67, v67, v71
	v_xor_b32_e32 v71, 4, v215
	v_cmp_lt_i32_e32 vcc, v71, v70
	s_nop 1
	v_cndmask_b32_e32 v71, v215, v71, vcc
	v_lshlrev_b32_e32 v108, 2, v71
	ds_bpermute_b32 v71, v108, v67
	s_waitcnt lgkmcnt(0)
	v_add_f32_e32 v67, v67, v71
	v_xor_b32_e32 v71, 2, v215
	v_cmp_lt_i32_e32 vcc, v71, v70
	s_nop 1
	v_cndmask_b32_e32 v71, v215, v71, vcc
	v_lshlrev_b32_e32 v109, 2, v71
	ds_bpermute_b32 v71, v109, v67
	s_waitcnt lgkmcnt(0)
	v_add_f32_e32 v67, v67, v71
	v_xor_b32_e32 v71, 1, v215
	v_cmp_lt_i32_e32 vcc, v71, v70
	s_nop 1
	v_cndmask_b32_e32 v70, v215, v71, vcc
	v_lshlrev_b32_e32 v111, 2, v70
	ds_bpermute_b32 v70, v111, v67
	s_waitcnt lgkmcnt(0)
	v_add_f32_e32 v67, v67, v70
	v_fmamk_f32 v67, v67, 0x3a000000, v212
	v_mul_f32_e32 v70, 0x4b800000, v67
	v_cmp_gt_f32_e32 vcc, s3, v67
	s_nop 1
	v_cndmask_b32_e32 v67, v67, v70, vcc
	v_rsq_f32_e32 v67, v67
	s_nop 0
	v_mul_f32_e32 v70, 0x45800000, v67
	v_cndmask_b32_e32 v70, v67, v70, vcc
	v_pk_mul_f32 v[94:95], v[94:95], v[70:71] op_sel_hi:[1,0]
	v_pk_mul_f32 v[100:101], v[100:101], v[70:71] op_sel_hi:[1,0]
	v_pk_fma_f32 v[58:59], v[6:7], v[94:95], v[58:59]
	v_pk_mul_f32 v[96:97], v[96:97], v[70:71] op_sel_hi:[1,0]
	v_pk_mul_f32 v[92:93], v[92:93], v[70:71] op_sel_hi:[1,0]
	v_mul_f32_e32 v71, v59, v59
	v_pk_fma_f32 v[62:63], v[2:3], v[100:101], v[62:63]
	v_pk_fma_f32 v[60:61], v[8:9], v[92:93], v[60:61]
	v_fmac_f32_e32 v71, v58, v58
	v_mul_f32_e32 v67, v63, v63
	v_fmac_f32_e32 v71, v60, v60
	v_pk_fma_f32 v[64:65], v[4:5], v[96:97], v[64:65]
	v_fmac_f32_e32 v67, v62, v62
	v_fmac_f32_e32 v71, v61, v61
	v_fmac_f32_e32 v67, v64, v64
	v_pk_mul_f32 v[90:91], v[90:91], v[70:71] op_sel_hi:[1,0]
	v_fmac_f32_e32 v67, v65, v65
	v_pk_fma_f32 v[54:55], v[10:11], v[90:91], v[54:55]
	v_add_f32_e32 v67, v67, v71
	v_pk_mul_f32 v[86:87], v[86:87], v[70:71] op_sel_hi:[1,0]
	v_mul_f32_e32 v71, v55, v55
	v_pk_fma_f32 v[56:57], v[12:13], v[86:87], v[56:57]
	v_fmac_f32_e32 v71, v54, v54
	v_fmac_f32_e32 v71, v56, v56
	v_fmac_f32_e32 v71, v57, v57
	v_pk_mul_f32 v[86:87], v[88:89], v[70:71] op_sel_hi:[1,0]
	v_add_f32_e32 v67, v71, v67
	v_pk_fma_f32 v[50:51], v[14:15], v[86:87], v[50:51]
	v_pk_mul_f32 v[84:85], v[84:85], v[70:71] op_sel_hi:[1,0]
	v_mul_f32_e32 v71, v51, v51
	v_pk_fma_f32 v[52:53], v[16:17], v[84:85], v[52:53]
	v_fmac_f32_e32 v71, v50, v50
	v_fmac_f32_e32 v71, v52, v52
	v_fmac_f32_e32 v71, v53, v53
	v_pk_mul_f32 v[80:81], v[80:81], v[70:71] op_sel_hi:[1,0]
	v_pk_mul_f32 v[76:77], v[76:77], v[70:71] op_sel_hi:[1,0]
	v_pk_fma_f32 v[46:47], v[18:19], v[80:81], v[46:47]
	v_pk_mul_f32 v[78:79], v[78:79], v[70:71] op_sel_hi:[1,0]
	v_pk_fma_f32 v[42:43], v[22:23], v[76:77], v[42:43]
	v_pk_mul_f32 v[82:83], v[82:83], v[70:71] op_sel_hi:[1,0]
	v_pk_fma_f32 v[44:45], v[24:25], v[78:79], v[44:45]
	v_mov_b32_e32 v78, v43
	v_mov_b32_e32 v79, v47
	v_pk_fma_f32 v[48:49], v[20:21], v[82:83], v[48:49]
	v_mov_b32_e32 v76, v42
	v_mov_b32_e32 v77, v46
	v_pk_mul_f32 v[78:79], v[78:79], v[78:79]
	v_pk_mul_f32 v[72:73], v[72:73], v[70:71] op_sel_hi:[1,0]
	v_pk_fma_f32 v[76:77], v[76:77], v[76:77], v[78:79]
	v_mov_b32_e32 v78, v44
	v_mov_b32_e32 v79, v48
	v_pk_fma_f32 v[76:77], v[78:79], v[78:79], v[76:77]
	v_mov_b32_e32 v78, v45
	v_mov_b32_e32 v79, v49
	v_add_f32_e32 v67, v71, v67
	v_pk_fma_f32 v[76:77], v[78:79], v[78:79], v[76:77]
	v_pk_mul_f32 v[74:75], v[74:75], v[70:71] op_sel_hi:[1,0]
	v_pk_fma_f32 v[38:39], v[26:27], v[72:73], v[38:39]
	v_pk_mul_f32 v[72:73], v[104:105], v[70:71] op_sel_hi:[1,0]
	v_pk_mul_f32 v[70:71], v[102:103], v[70:71] op_sel_hi:[1,0]
	v_add_f32_e32 v67, v77, v67
	v_pk_fma_f32 v[34:35], v[30:31], v[70:71], v[34:35]
	v_add_f32_e32 v67, v76, v67
	v_mov_b32_e32 v76, v35
	v_mov_b32_e32 v77, v39
	v_pk_fma_f32 v[40:41], v[28:29], v[74:75], v[40:41]
	v_pk_fma_f32 v[36:37], v[32:33], v[72:73], v[36:37]
	v_mov_b32_e32 v74, v34
	v_mov_b32_e32 v75, v38
	v_pk_mul_f32 v[76:77], v[76:77], v[76:77]
	v_mov_b32_e32 v72, v36
	v_mov_b32_e32 v73, v40
	v_pk_fma_f32 v[74:75], v[74:75], v[74:75], v[76:77]
	v_mov_b32_e32 v70, v37
	v_mov_b32_e32 v71, v41
	v_pk_fma_f32 v[72:73], v[72:73], v[72:73], v[74:75]
	s_nop 0
	v_pk_fma_f32 v[70:71], v[70:71], v[70:71], v[72:73]
	s_nop 0
	v_add_f32_e32 v67, v71, v67
	v_add_f32_e32 v67, v70, v67
	ds_bpermute_b32 v70, v99, v67
	v_mov_b32_e32 v99, v1
	v_lshl_add_u64 v[68:69], v[68:69], 0, v[98:99]
	global_store_dwordx4 v[68:69], v[62:65], off
	global_store_dwordx4 v[68:69], v[58:61], off offset:1024
	global_store_dwordx4 v[68:69], v[54:57], off offset:2048
	global_store_dwordx4 v[68:69], v[50:53], off offset:3072
	v_add_co_u32_e32 v68, vcc, s2, v68
	s_waitcnt lgkmcnt(0)
	v_add_f32_e32 v67, v67, v70
	ds_bpermute_b32 v70, v106, v67
	v_addc_co_u32_e32 v69, vcc, 0, v69, vcc
	global_store_dwordx4 v[68:69], v[46:49], off
	global_store_dwordx4 v[68:69], v[42:45], off offset:1024
	global_store_dwordx4 v[68:69], v[38:41], off offset:2048
	global_store_dwordx4 v[68:69], v[34:37], off offset:3072
	s_waitcnt lgkmcnt(0)
	v_add_f32_e32 v67, v67, v70
	ds_bpermute_b32 v70, v107, v67
	s_waitcnt lgkmcnt(0)
	v_add_f32_e32 v67, v67, v70
	ds_bpermute_b32 v70, v108, v67
	s_waitcnt lgkmcnt(0)
	v_add_f32_e32 v67, v67, v70
	ds_bpermute_b32 v70, v109, v67
	s_waitcnt lgkmcnt(0)
	v_add_f32_e32 v67, v67, v70
	ds_bpermute_b32 v70, v111, v67
	s_waitcnt lgkmcnt(0)
	v_add_f32_e32 v67, v67, v70
	v_fmamk_f32 v67, v67, 0x3a000000, v212
	v_mul_f32_e32 v70, 0x4b800000, v67
	v_cmp_gt_f32_e32 vcc, s3, v67
	s_mov_b64 s[2:3], 0x1cc00000
	s_nop 0
	v_cndmask_b32_e32 v67, v67, v70, vcc
	v_rsq_f32_e32 v67, v67
	s_nop 0
	v_mul_f32_e32 v68, 0x45800000, v67
	v_cndmask_b32_e32 v67, v67, v68, vcc
	v_lshl_add_u64 v[68:69], s[34:35], 0, v[0:1]
	v_lshlrev_b32_e32 v0, 1, v110
	v_lshl_add_u64 v[68:69], v[68:69], 0, v[0:1]
	v_lshl_add_u64 v[70:71], v[68:69], 0, s[2:3]
	v_mul_f32_e32 v0, v62, v67
	v_mul_f32_e32 v62, v63, v67
	s_mov_b32 s2, 0x1cc00000
	v_cvt_pk_bf16_f32 v62, v0, v62
	v_mul_f32_e32 v0, v64, v67
	v_mul_f32_e32 v63, v65, v67
	v_add_co_u32_e32 v64, vcc, s2, v68
	v_cvt_pk_bf16_f32 v63, v0, v63
	v_mul_f32_e32 v0, v58, v67
	s_nop 0
	v_addc_co_u32_e32 v65, vcc, 0, v69, vcc
	v_mul_f32_e32 v58, v59, v67
	global_store_dwordx2 v[64:65], v[62:63], off
	v_cvt_pk_bf16_f32 v58, v0, v58
	v_mul_f32_e32 v0, v60, v67
	v_mul_f32_e32 v59, v61, v67
	v_cvt_pk_bf16_f32 v59, v0, v59
	v_mul_f32_e32 v0, v54, v67
	v_mul_f32_e32 v54, v55, v67
	global_store_dwordx2 v[70:71], v[58:59], off offset:512
	v_cvt_pk_bf16_f32 v54, v0, v54
	v_mul_f32_e32 v0, v56, v67
	v_mul_f32_e32 v55, v57, v67
	v_cvt_pk_bf16_f32 v55, v0, v55
	v_mul_f32_e32 v0, v50, v67
	v_mul_f32_e32 v50, v51, v67
	global_store_dwordx2 v[70:71], v[54:55], off offset:1024
	v_cvt_pk_bf16_f32 v50, v0, v50
	v_mul_f32_e32 v0, v52, v67
	v_mul_f32_e32 v51, v53, v67
	v_cvt_pk_bf16_f32 v51, v0, v51
	v_mul_f32_e32 v0, v46, v67
	v_mul_f32_e32 v46, v47, v67
	global_store_dwordx2 v[70:71], v[50:51], off offset:1536
	v_cvt_pk_bf16_f32 v46, v0, v46
	v_mul_f32_e32 v0, v48, v67
	v_mul_f32_e32 v47, v49, v67
	v_cvt_pk_bf16_f32 v47, v0, v47
	v_mul_f32_e32 v0, v42, v67
	v_mul_f32_e32 v42, v43, v67
	global_store_dwordx2 v[70:71], v[46:47], off offset:2048
	v_cvt_pk_bf16_f32 v42, v0, v42
	v_mul_f32_e32 v0, v44, v67
	v_mul_f32_e32 v43, v45, v67
	v_cvt_pk_bf16_f32 v43, v0, v43
	v_mul_f32_e32 v0, v38, v67
	v_mul_f32_e32 v38, v39, v67
	global_store_dwordx2 v[70:71], v[42:43], off offset:2560
	v_cvt_pk_bf16_f32 v38, v0, v38
	v_mul_f32_e32 v0, v40, v67
	v_mul_f32_e32 v39, v41, v67
	v_cvt_pk_bf16_f32 v39, v0, v39
	v_mul_f32_e32 v0, v34, v67
	v_mul_f32_e32 v34, v35, v67
	v_mul_f32_e32 v35, v37, v67
	global_store_dwordx2 v[70:71], v[38:39], off offset:3072
	v_cvt_pk_bf16_f32 v34, v0, v34
	v_mul_f32_e32 v0, v36, v67
	v_cvt_pk_bf16_f32 v35, v0, v35
	global_store_dwordx2 v[70:71], v[34:35], off offset:3584
